# peeled first K iteration per tile with C=0 MFMAs replaces the 128 accumulator-clearing v_mov (all four plain GEMM loops)
# baseline (speedup 1.0000x reference)
; #define PG8_STAGE(bufoff, gbase, voff) do { _Pragma("unroll") for (int _i = 0; _i < 2; ++_i) \
;         __builtin_amdgcn_global_load_lds((const unsigned*)((const char*)(gbase) + (voff)[_i]), (PG8_LAS unsigned*)(lds + (bufoff) + ldsw + _i * 8192), 16, 0, 0); } while (0)
; #define PG8_LDA(dst, b, h) do { _Pragma("unroll") for (int m = 0; m < 4; ++m) _Pragma("unroll") for (int k = 0; k < 2; ++k) dst[m][k] = *(const PG8_LAS bf16x8*)(lds + PG8_SA(b, h) + aoff + m * 2048 + k * 1024); } while (0)
; #define PG8_LDB(dst, b, h) do { _Pragma("unroll") for (int n = 0; n < 2; ++n) _Pragma("unroll") for (int k = 0; k < 2; ++k) dst[n][k] = *(const PG8_LAS bf16x8*)(lds + PG8_SB(b, h) + boff + n * 2048 + k * 1024); } while (0)
; #define PG8_MMA(ai, bj, At, Bt) do { __builtin_amdgcn_s_setprio(1); _Pragma("unroll") for (int m = 0; m < 4; ++m) _Pragma("unroll") for (int n = 0; n < 2; ++n) _Pragma("unroll") for (int k = 0; k < 2; ++k) \
;         acc[ai][bj][m][n] = __builtin_amdgcn_mfma_f32_16x16x32_bf16(Bt[n][k], At[m][k], acc[ai][bj][m][n], 0, 0, 0); __builtin_amdgcn_s_setprio(0); } while (0)
; template <class Epi, class Sched, bool ALIGN_EPI = false, bool SP2 = false>
; __device__ __forceinline__ void gemm_phase(PG8_LAS unsigned char* lds, const Gemm g, const Sched& S, const Epi& E) {
;     ...
;         const bool has_next = S.next(ui + 1, nxt);
;         const char* nA = has_next ? (const char*)(nxt.seg ? g.A2 : g.A) + (size_t)nxt.pm * tstep : cA; const char* nB = has_next ? (const char*)(nxt.seg ? g.Bt2 : g.Bt) + (size_t)nxt.pn * tstep : cB;
;         for (int t = 0; t < nt; t += 2) {
;             const bool last = (t == nt - 2);
;             const char* a1 = cA + (size_t)(t + 1) * kstep;
;             const char* a2 = last ? nA : cA + (size_t)(t + 2) * kstep; const char* b2 = last ? nB : cB + (size_t)(t + 2) * kstep;
;             const char* a3 = a2 + kstep; const char* b3 = b2 + kstep;
;             if (last && has_next) S.a_ready(nxt);
;             if constexpr (SP2) {
;             PG8_LDB(B0, 0, 0); PG8_LDB(B1, 0, 1); PG8_SCHED; PG8_LDA(At, 0, 0); PG8_STAGE(PG8_SA(1, 1), a1 + hstep, voffA);
;             PG8_WAIT_V(8); PG8_WAIT_L(0); PG8_BAR; PG8_MMA(0, 0, At, B0); PG8_MMA(0, 1, At, B1); PG8_BAR; PG8_SCHED;
;             PG8_LDA(At, 0, 1); PG8_STAGE(PG8_SB(0, 0), b2, voffB); PG8_STAGE(PG8_SB(0, 1), b2 + hstep, voffB); PG8_STAGE(PG8_SA(0, 0), a2, voffA);
.LBB0_130:
	s_ashr_i32 s41, s40, 31
	s_lshl_b64 s[42:43], s[40:41], 20
	s_add_u32 s42, s35, s42
	s_addc_u32 s43, s54, s43
	s_and_b64 s[44:45], s[6:7], exec
	s_cselect_b32 s33, s43, s49
	s_cselect_b32 s41, s42, s48
	s_ashr_i32 s39, s38, 31
	s_lshl_b64 s[44:45], s[38:39], 20
	s_add_u32 s44, s55, s44
	s_addc_u32 s45, s56, s45
	s_and_b64 s[52:53], s[6:7], exec
	s_cselect_b32 s39, s45, s51
	s_cselect_b32 s47, s44, s50
	s_add_u32 s48, s48, 0x80080
	s_addc_u32 s49, s49, 0
	s_add_u32 s71, s50, 0x100
	v_mov_b32_e32 v28, 0
	s_addc_u32 s72, s51, 0
	s_mov_b32 s73, -2
	ds_read_b128 v[148:151], v156
	ds_read_b128 v[162:165], v157
	ds_read_b128 v[166:169], v156 offset:2048
	ds_read_b128 v[170:173], v157 offset:2048
	ds_read_b128 v[174:177], v156 offset:16384
	ds_read_b128 v[178:181], v157 offset:16384
	ds_read_b128 v[182:185], v156 offset:18432
	ds_read_b128 v[186:189], v157 offset:18432
	s_add_u32 s36, s48, 0xfff80080
	s_addc_u32 s37, s49, -1
	s_cmp_eq_u32 s73, 28
	s_cselect_b32 s53, s33, s37
	s_cselect_b32 s52, s41, s36
	s_cselect_b32 s51, s39, s72
	s_cselect_b32 s50, s47, s71
	v_lshl_add_u64 v[152:153], s[48:49], 0, v[138:139]
	s_add_i32 m0, s60, 0xc000
	ds_read_b128 v[190:193], v158
	ds_read_b128 v[194:197], v242
	ds_read_b128 v[198:201], v158 offset:2048
	ds_read_b128 v[202:205], v242 offset:2048
	ds_read_b128 v[206:209], v158 offset:4096
	ds_read_b128 v[210:213], v242 offset:4096
	ds_read_b128 v[214:217], v158 offset:6144
	ds_read_b128 v[218:221], v242 offset:6144
	global_load_lds_dwordx4 v[152:153], off
	v_lshl_add_u64 v[152:153], s[48:49], 0, v[140:141]
	s_add_i32 m0, s60, 0xe000
	s_nop 0
	global_load_lds_dwordx4 v[152:153], off
	s_waitcnt vmcnt(8)
	s_waitcnt lgkmcnt(0)
	s_barrier
	s_setprio 1
	s_waitcnt lgkmcnt(0)
	v_mfma_f32_16x16x32_bf16 v[76:79], v[148:151], v[190:193], 0
	v_mfma_f32_16x16x32_bf16 v[72:75], v[166:169], v[190:193], 0
	v_mfma_f32_16x16x32_bf16 v[68:71], v[148:151], v[198:201], 0
	v_mfma_f32_16x16x32_bf16 v[64:67], v[166:169], v[198:201], 0
	v_mfma_f32_16x16x32_bf16 v[60:63], v[148:151], v[206:209], 0
	v_mfma_f32_16x16x32_bf16 v[52:55], v[166:169], v[206:209], 0
	v_mfma_f32_16x16x32_bf16 v[44:47], v[148:151], v[214:217], 0
	v_mfma_f32_16x16x32_bf16 v[40:43], v[166:169], v[214:217], 0
	v_mfma_f32_16x16x32_bf16 v[76:79], v[162:165], v[194:197], v[76:79]
	v_mfma_f32_16x16x32_bf16 v[72:75], v[170:173], v[194:197], v[72:75]
	v_mfma_f32_16x16x32_bf16 v[68:71], v[162:165], v[202:205], v[68:71]
	v_mfma_f32_16x16x32_bf16 v[64:67], v[170:173], v[202:205], v[64:67]
	v_mfma_f32_16x16x32_bf16 v[60:63], v[162:165], v[210:213], v[60:63]
	v_mfma_f32_16x16x32_bf16 v[52:55], v[170:173], v[210:213], v[52:55]
	v_mfma_f32_16x16x32_bf16 v[44:47], v[162:165], v[218:221], v[44:47]
	v_mfma_f32_16x16x32_bf16 v[40:43], v[170:173], v[218:221], v[40:43]
	s_setprio 0
	s_setprio 1
	v_mfma_f32_16x16x32_bf16 v[124:127], v[174:177], v[190:193], 0
	v_mfma_f32_16x16x32_bf16 v[120:123], v[182:185], v[190:193], 0
	v_mfma_f32_16x16x32_bf16 v[116:119], v[174:177], v[198:201], 0
	v_mfma_f32_16x16x32_bf16 v[112:115], v[182:185], v[198:201], 0
	v_mfma_f32_16x16x32_bf16 v[108:111], v[174:177], v[206:209], 0
	v_mfma_f32_16x16x32_bf16 v[104:107], v[182:185], v[206:209], 0
	v_mfma_f32_16x16x32_bf16 v[100:103], v[174:177], v[214:217], 0
	v_mfma_f32_16x16x32_bf16 v[96:99], v[182:185], v[214:217], 0
	v_mfma_f32_16x16x32_bf16 v[124:127], v[178:181], v[194:197], v[124:127]
	v_mfma_f32_16x16x32_bf16 v[120:123], v[186:189], v[194:197], v[120:123]
	v_mfma_f32_16x16x32_bf16 v[116:119], v[178:181], v[202:205], v[116:119]
	v_mfma_f32_16x16x32_bf16 v[112:115], v[186:189], v[202:205], v[112:115]
	v_mfma_f32_16x16x32_bf16 v[108:111], v[178:181], v[210:213], v[108:111]
	v_mfma_f32_16x16x32_bf16 v[104:107], v[186:189], v[210:213], v[104:107]
	v_mfma_f32_16x16x32_bf16 v[100:103], v[178:181], v[218:221], v[100:103]
	v_mfma_f32_16x16x32_bf16 v[96:99], v[186:189], v[218:221], v[96:99]
	s_setprio 0
	s_barrier
	s_add_i32 s36, s68, s57
	v_lshl_add_u64 v[152:153], s[50:51], 0, v[132:133]
	s_mov_b32 m0, s36
	ds_read_b128 v[190:193], v158 offset:16384
	ds_read_b128 v[194:197], v242 offset:16384
	ds_read_b128 v[198:201], v158 offset:18432
	ds_read_b128 v[202:205], v242 offset:18432
	ds_read_b128 v[206:209], v158 offset:20480
	ds_read_b128 v[210:213], v242 offset:20480
	ds_read_b128 v[214:217], v158 offset:22528
	ds_read_b128 v[218:221], v242 offset:22528
	global_load_lds_dwordx4 v[152:153], off
	s_add_i32 m0, s36, 0x2000
	s_add_u32 s74, s50, 0x80000
	v_lshl_add_u64 v[222:223], s[50:51], 0, v[128:129]
	s_addc_u32 s75, s51, 0
	s_add_i32 s36, s69, s57
	global_load_lds_dwordx4 v[222:223], off
	v_lshl_add_u64 v[224:225], s[74:75], 0, v[132:133]
	s_mov_b32 m0, s36
	v_lshl_add_u64 v[226:227], s[52:53], 0, v[130:131]
	global_load_lds_dwordx4 v[224:225], off
	v_lshl_add_u64 v[224:225], s[74:75], 0, v[128:129]
	s_add_i32 m0, s36, 0x2000
	s_nop 0
	global_load_lds_dwordx4 v[224:225], off
	v_lshl_add_u64 v[224:225], s[52:53], 0, v[134:135]
	s_mov_b32 m0, s60
	s_nop 0
	global_load_lds_dwordx4 v[224:225], off
	s_mov_b32 m0, s61
	s_nop 0
	global_load_lds_dwordx4 v[226:227], off
	s_waitcnt vmcnt(8)
	s_waitcnt lgkmcnt(0)
	s_barrier
; #define PG8_STAGE(bufoff, gbase, voff) do { _Pragma("unroll") for (int _i = 0; _i < 2; ++_i) \
;         __builtin_amdgcn_global_load_lds((const unsigned*)((const char*)(gbase) + (voff)[_i]), (PG8_LAS unsigned*)(lds + (bufoff) + ldsw + _i * 8192), 16, 0, 0); } while (0)
; #define PG8_LDA(dst, b, h) do { _Pragma("unroll") for (int m = 0; m < 4; ++m) _Pragma("unroll") for (int k = 0; k < 2; ++k) dst[m][k] = *(const PG8_LAS bf16x8*)(lds + PG8_SA(b, h) + aoff + m * 2048 + k * 1024); } while (0)
; #define PG8_LDB(dst, b, h) do { _Pragma("unroll") for (int n = 0; n < 2; ++n) _Pragma("unroll") for (int k = 0; k < 2; ++k) dst[n][k] = *(const PG8_LAS bf16x8*)(lds + PG8_SB(b, h) + boff + n * 2048 + k * 1024); } while (0)
; #define PG8_MMA(ai, bj, At, Bt) do { __builtin_amdgcn_s_setprio(1); _Pragma("unroll") for (int m = 0; m < 4; ++m) _Pragma("unroll") for (int n = 0; n < 2; ++n) _Pragma("unroll") for (int k = 0; k < 2; ++k) \
;         acc[ai][bj][m][n] = __builtin_amdgcn_mfma_f32_16x16x32_bf16(Bt[n][k], At[m][k], acc[ai][bj][m][n], 0, 0, 0); __builtin_amdgcn_s_setprio(0); } while (0)
; #define PG8_WAIT_V(n) asm volatile("s_waitcnt vmcnt(" #n ")" ::: "memory")
; #define PG8_WAIT_L(n) asm volatile("s_waitcnt lgkmcnt(" #n ")" ::: "memory")
; #define PG8_BAR __builtin_amdgcn_s_barrier()
; #define PG8_SCHED __builtin_amdgcn_sched_barrier(0)
; template <class Epi, class Sched, bool ALIGN_EPI = false, bool SP2 = false>
; __device__ __forceinline__ void gemm_phase(PG8_LAS unsigned char* lds, const Gemm g, const Sched& S, const Epi& E) {
;     ...
;             PG8_WAIT_V(8); PG8_WAIT_L(0); PG8_BAR; PG8_MMA(1, 0, At, B0); PG8_MMA(1, 1, At, B1); PG8_BAR; PG8_SCHED;
;             PG8_LDB(B0, 1, 0); PG8_LDB(B1, 1, 1); PG8_SCHED; PG8_LDA(At, 1, 0); PG8_STAGE(PG8_SA(0, 1), a2 + hstep, voffA);
;             PG8_WAIT_V(8); PG8_WAIT_L(0); PG8_BAR; PG8_MMA(0, 0, At, B0); PG8_MMA(0, 1, At, B1); PG8_BAR; PG8_SCHED;
	s_setprio 1
	s_waitcnt lgkmcnt(0)
	v_mfma_f32_16x16x32_bf16 v[32:35], v[148:151], v[190:193], 0
	v_mfma_f32_16x16x32_bf16 v[24:27], v[166:169], v[190:193], 0
	v_mfma_f32_16x16x32_bf16 v[20:23], v[148:151], v[198:201], 0
	v_mfma_f32_16x16x32_bf16 v[16:19], v[166:169], v[198:201], 0
	v_mfma_f32_16x16x32_bf16 v[12:15], v[148:151], v[206:209], 0
	v_mfma_f32_16x16x32_bf16 v[8:11], v[166:169], v[206:209], 0
	v_mfma_f32_16x16x32_bf16 v[4:7], v[148:151], v[214:217], 0
	v_mfma_f32_16x16x32_bf16 v[0:3], v[166:169], v[214:217], 0
	v_mfma_f32_16x16x32_bf16 v[32:35], v[162:165], v[194:197], v[32:35]
	v_mfma_f32_16x16x32_bf16 v[24:27], v[170:173], v[194:197], v[24:27]
	v_mfma_f32_16x16x32_bf16 v[20:23], v[162:165], v[202:205], v[20:23]
	v_mfma_f32_16x16x32_bf16 v[16:19], v[170:173], v[202:205], v[16:19]
	v_mfma_f32_16x16x32_bf16 v[12:15], v[162:165], v[210:213], v[12:15]
	v_mfma_f32_16x16x32_bf16 v[8:11], v[170:173], v[210:213], v[8:11]
	v_mfma_f32_16x16x32_bf16 v[4:7], v[162:165], v[218:221], v[4:7]
	v_mfma_f32_16x16x32_bf16 v[0:3], v[170:173], v[218:221], v[0:3]
	s_setprio 0
	s_setprio 1
	v_mfma_f32_16x16x32_bf16 v[92:95], v[174:177], v[190:193], 0
	v_mfma_f32_16x16x32_bf16 v[88:91], v[182:185], v[190:193], 0
	v_mfma_f32_16x16x32_bf16 v[84:87], v[174:177], v[198:201], 0
	v_mfma_f32_16x16x32_bf16 v[80:83], v[182:185], v[198:201], 0
	v_mfma_f32_16x16x32_bf16 v[56:59], v[174:177], v[206:209], 0
	v_mfma_f32_16x16x32_bf16 v[48:51], v[182:185], v[206:209], 0
	v_mfma_f32_16x16x32_bf16 v[36:39], v[174:177], v[214:217], 0
	v_mfma_f32_16x16x32_bf16 v[28:31], v[182:185], v[214:217], 0
	v_mfma_f32_16x16x32_bf16 v[92:95], v[178:181], v[194:197], v[92:95]
	v_mfma_f32_16x16x32_bf16 v[88:91], v[186:189], v[194:197], v[88:91]
	v_mfma_f32_16x16x32_bf16 v[84:87], v[178:181], v[202:205], v[84:87]
	v_mfma_f32_16x16x32_bf16 v[80:83], v[186:189], v[202:205], v[80:83]
	v_mfma_f32_16x16x32_bf16 v[56:59], v[178:181], v[210:213], v[56:59]
	v_mfma_f32_16x16x32_bf16 v[48:51], v[186:189], v[210:213], v[48:51]
	v_mfma_f32_16x16x32_bf16 v[36:39], v[178:181], v[218:221], v[36:39]
	v_mfma_f32_16x16x32_bf16 v[28:31], v[186:189], v[218:221], v[28:31]
	s_setprio 0
	s_barrier
	s_add_i32 s36, 0, 0x18000
	v_add_u32_e32 v161, s36, v154
	s_add_i32 s37, 0, 0x1c000
	ds_read_b128 v[148:151], v156 offset:32768
	ds_read_b128 v[162:165], v157 offset:32768
	ds_read_b128 v[166:169], v156 offset:34816
	ds_read_b128 v[170:173], v157 offset:34816
	v_add_u32_e32 v161, s37, v154
	ds_read_b128 v[174:177], v156 offset:49152
	ds_read_b128 v[178:181], v157 offset:49152
	ds_read_b128 v[182:185], v156 offset:51200
	ds_read_b128 v[186:189], v157 offset:51200
	s_add_u32 s52, s52, 0x80000
	s_addc_u32 s53, s53, 0
	s_mov_b32 m0, s62
	v_lshl_add_u64 v[228:229], s[52:53], 0, v[134:135]
	ds_read_b128 v[190:193], v158 offset:32768
	ds_read_b128 v[194:197], v242 offset:32768
	ds_read_b128 v[198:201], v158 offset:34816
	ds_read_b128 v[202:205], v242 offset:34816
	ds_read_b128 v[206:209], v158 offset:36864
	ds_read_b128 v[210:213], v242 offset:36864
	ds_read_b128 v[214:217], v158 offset:38912
	ds_read_b128 v[218:221], v242 offset:38912
	global_load_lds_dwordx4 v[228:229], off
	v_lshl_add_u64 v[228:229], s[52:53], 0, v[130:131]
	s_mov_b32 m0, s63
	s_nop 0
	global_load_lds_dwordx4 v[228:229], off
	s_waitcnt vmcnt(8)
	s_waitcnt lgkmcnt(0)
	s_barrier
	s_setprio 1
	s_waitcnt lgkmcnt(0)
	v_mfma_f32_16x16x32_bf16 v[76:79], v[148:151], v[190:193], v[76:79]
	v_mfma_f32_16x16x32_bf16 v[72:75], v[166:169], v[190:193], v[72:75]
	v_mfma_f32_16x16x32_bf16 v[68:71], v[148:151], v[198:201], v[68:71]
	v_mfma_f32_16x16x32_bf16 v[64:67], v[166:169], v[198:201], v[64:67]
	v_mfma_f32_16x16x32_bf16 v[60:63], v[148:151], v[206:209], v[60:63]
	v_mfma_f32_16x16x32_bf16 v[52:55], v[166:169], v[206:209], v[52:55]
	v_mfma_f32_16x16x32_bf16 v[44:47], v[148:151], v[214:217], v[44:47]
	v_mfma_f32_16x16x32_bf16 v[40:43], v[166:169], v[214:217], v[40:43]
	v_mfma_f32_16x16x32_bf16 v[76:79], v[162:165], v[194:197], v[76:79]
	v_mfma_f32_16x16x32_bf16 v[72:75], v[170:173], v[194:197], v[72:75]
	v_mfma_f32_16x16x32_bf16 v[68:71], v[162:165], v[202:205], v[68:71]
	v_mfma_f32_16x16x32_bf16 v[64:67], v[170:173], v[202:205], v[64:67]
	v_mfma_f32_16x16x32_bf16 v[60:63], v[162:165], v[210:213], v[60:63]
	v_mfma_f32_16x16x32_bf16 v[52:55], v[170:173], v[210:213], v[52:55]
	v_mfma_f32_16x16x32_bf16 v[44:47], v[162:165], v[218:221], v[44:47]
	v_mfma_f32_16x16x32_bf16 v[40:43], v[170:173], v[218:221], v[40:43]
	s_setprio 0
	s_setprio 1
	v_mfma_f32_16x16x32_bf16 v[124:127], v[174:177], v[190:193], v[124:127]
	v_mfma_f32_16x16x32_bf16 v[120:123], v[182:185], v[190:193], v[120:123]
	v_mfma_f32_16x16x32_bf16 v[116:119], v[174:177], v[198:201], v[116:119]
	v_mfma_f32_16x16x32_bf16 v[112:115], v[182:185], v[198:201], v[112:115]
	v_mfma_f32_16x16x32_bf16 v[108:111], v[174:177], v[206:209], v[108:111]
	v_mfma_f32_16x16x32_bf16 v[104:107], v[182:185], v[206:209], v[104:107]
	v_mfma_f32_16x16x32_bf16 v[100:103], v[174:177], v[214:217], v[100:103]
	v_mfma_f32_16x16x32_bf16 v[96:99], v[182:185], v[214:217], v[96:99]
	v_mfma_f32_16x16x32_bf16 v[124:127], v[178:181], v[194:197], v[124:127]
	v_mfma_f32_16x16x32_bf16 v[120:123], v[186:189], v[194:197], v[120:123]
	v_mfma_f32_16x16x32_bf16 v[116:119], v[178:181], v[202:205], v[116:119]
	v_mfma_f32_16x16x32_bf16 v[112:115], v[186:189], v[202:205], v[112:115]
	v_mfma_f32_16x16x32_bf16 v[108:111], v[178:181], v[210:213], v[108:111]
	v_mfma_f32_16x16x32_bf16 v[104:107], v[186:189], v[210:213], v[104:107]
	v_mfma_f32_16x16x32_bf16 v[100:103], v[178:181], v[218:221], v[100:103]
	v_mfma_f32_16x16x32_bf16 v[96:99], v[186:189], v[218:221], v[96:99]
	s_setprio 0
	s_barrier
; #define PG8_STAGE(bufoff, gbase, voff) do { _Pragma("unroll") for (int _i = 0; _i < 2; ++_i) \
;         __builtin_amdgcn_global_load_lds((const unsigned*)((const char*)(gbase) + (voff)[_i]), (PG8_LAS unsigned*)(lds + (bufoff) + ldsw + _i * 8192), 16, 0, 0); } while (0)
; #define PG8_LDA(dst, b, h) do { _Pragma("unroll") for (int m = 0; m < 4; ++m) _Pragma("unroll") for (int k = 0; k < 2; ++k) dst[m][k] = *(const PG8_LAS bf16x8*)(lds + PG8_SA(b, h) + aoff + m * 2048 + k * 1024); } while (0)
; #define PG8_MMA(ai, bj, At, Bt) do { __builtin_amdgcn_s_setprio(1); _Pragma("unroll") for (int m = 0; m < 4; ++m) _Pragma("unroll") for (int n = 0; n < 2; ++n) _Pragma("unroll") for (int k = 0; k < 2; ++k) \
;         acc[ai][bj][m][n] = __builtin_amdgcn_mfma_f32_16x16x32_bf16(Bt[n][k], At[m][k], acc[ai][bj][m][n], 0, 0, 0); __builtin_amdgcn_s_setprio(0); } while (0)
; #define PG8_WAIT_V(n) asm volatile("s_waitcnt vmcnt(" #n ")" ::: "memory")
; #define PG8_WAIT_L(n) asm volatile("s_waitcnt lgkmcnt(" #n ")" ::: "memory")
; #define PG8_BAR __builtin_amdgcn_s_barrier()
; #define PG8_SCHED __builtin_amdgcn_sched_barrier(0)
; template <class Epi, class Sched, bool ALIGN_EPI = false, bool SP2 = false>
; __device__ __forceinline__ void gemm_phase(PG8_LAS unsigned char* lds, const Gemm g, const Sched& S, const Epi& E) {
;     ...
;         for (int t = 0; t < nt; t += 2) {
;     ...
;             PG8_LDA(At, 1, 1); PG8_STAGE(PG8_SB(1, 0), b3, voffB); PG8_STAGE(PG8_SB(1, 1), b3 + hstep, voffB); PG8_STAGE(PG8_SA(1, 0), a3, voffA);
;             PG8_WAIT_V(8); PG8_WAIT_L(0); PG8_BAR; PG8_MMA(1, 0, At, B0); PG8_MMA(1, 1, At, B1); PG8_BAR; PG8_SCHED;
	s_add_i32 s36, s36, s57
	v_lshl_add_u64 v[152:153], v[152:153], 0, s[12:13]
	s_mov_b32 m0, s36
	ds_read_b128 v[190:193], v158 offset:49152
	ds_read_b128 v[194:197], v242 offset:49152
	ds_read_b128 v[198:201], v158 offset:51200
	ds_read_b128 v[202:205], v242 offset:51200
	ds_read_b128 v[206:209], v158 offset:53248
	ds_read_b128 v[210:213], v242 offset:53248
	ds_read_b128 v[214:217], v158 offset:55296
	ds_read_b128 v[218:221], v242 offset:55296
	global_load_lds_dwordx4 v[152:153], off
	s_add_i32 m0, s36, 0x2000
	s_add_u32 s50, s50, 0x80080
	v_lshl_add_u64 v[152:153], v[222:223], 0, s[12:13]
	s_addc_u32 s51, s51, 0
	s_add_i32 s36, s37, s57
	global_load_lds_dwordx4 v[152:153], off
	v_lshl_add_u64 v[152:153], s[50:51], 0, v[132:133]
	s_mov_b32 m0, s36
	s_nop 0
	global_load_lds_dwordx4 v[152:153], off
	v_lshl_add_u64 v[152:153], s[50:51], 0, v[128:129]
	s_add_i32 m0, s36, 0x2000
	s_nop 0
	global_load_lds_dwordx4 v[152:153], off
	v_lshl_add_u64 v[152:153], v[224:225], 0, s[12:13]
	s_mov_b32 m0, s65
	s_nop 0
	global_load_lds_dwordx4 v[152:153], off
	v_lshl_add_u64 v[152:153], v[226:227], 0, s[12:13]
	s_mov_b32 m0, s66
	s_nop 0
	global_load_lds_dwordx4 v[152:153], off
	s_waitcnt vmcnt(8)
	s_waitcnt lgkmcnt(0)
	s_barrier
	s_setprio 1
	s_waitcnt lgkmcnt(0)
	v_mfma_f32_16x16x32_bf16 v[32:35], v[148:151], v[190:193], v[32:35]
	v_mfma_f32_16x16x32_bf16 v[24:27], v[166:169], v[190:193], v[24:27]
	v_mfma_f32_16x16x32_bf16 v[20:23], v[148:151], v[198:201], v[20:23]
	v_mfma_f32_16x16x32_bf16 v[16:19], v[166:169], v[198:201], v[16:19]
	v_mfma_f32_16x16x32_bf16 v[12:15], v[148:151], v[206:209], v[12:15]
	v_mfma_f32_16x16x32_bf16 v[8:11], v[166:169], v[206:209], v[8:11]
	v_mfma_f32_16x16x32_bf16 v[4:7], v[148:151], v[214:217], v[4:7]
	v_mfma_f32_16x16x32_bf16 v[0:3], v[166:169], v[214:217], v[0:3]
	v_mfma_f32_16x16x32_bf16 v[32:35], v[162:165], v[194:197], v[32:35]
	v_mfma_f32_16x16x32_bf16 v[24:27], v[170:173], v[194:197], v[24:27]
	v_mfma_f32_16x16x32_bf16 v[20:23], v[162:165], v[202:205], v[20:23]
	v_mfma_f32_16x16x32_bf16 v[16:19], v[170:173], v[202:205], v[16:19]
	v_mfma_f32_16x16x32_bf16 v[12:15], v[162:165], v[210:213], v[12:15]
	v_mfma_f32_16x16x32_bf16 v[8:11], v[170:173], v[210:213], v[8:11]
	v_mfma_f32_16x16x32_bf16 v[4:7], v[162:165], v[218:221], v[4:7]
	v_mfma_f32_16x16x32_bf16 v[0:3], v[170:173], v[218:221], v[0:3]
	s_setprio 0
	s_setprio 1
	v_mfma_f32_16x16x32_bf16 v[92:95], v[174:177], v[190:193], v[92:95]
	v_mfma_f32_16x16x32_bf16 v[88:91], v[182:185], v[190:193], v[88:91]
	v_mfma_f32_16x16x32_bf16 v[84:87], v[174:177], v[198:201], v[84:87]
	v_mfma_f32_16x16x32_bf16 v[80:83], v[182:185], v[198:201], v[80:83]
	v_mfma_f32_16x16x32_bf16 v[56:59], v[174:177], v[206:209], v[56:59]
	v_mfma_f32_16x16x32_bf16 v[48:51], v[182:185], v[206:209], v[48:51]
	v_mfma_f32_16x16x32_bf16 v[36:39], v[174:177], v[214:217], v[36:39]
	v_mfma_f32_16x16x32_bf16 v[28:31], v[182:185], v[214:217], v[28:31]
	v_mfma_f32_16x16x32_bf16 v[92:95], v[178:181], v[194:197], v[92:95]
	v_mfma_f32_16x16x32_bf16 v[88:91], v[186:189], v[194:197], v[88:91]
	v_mfma_f32_16x16x32_bf16 v[84:87], v[178:181], v[202:205], v[84:87]
	v_mfma_f32_16x16x32_bf16 v[80:83], v[186:189], v[202:205], v[80:83]
	v_mfma_f32_16x16x32_bf16 v[56:59], v[178:181], v[210:213], v[56:59]
	v_mfma_f32_16x16x32_bf16 v[48:51], v[186:189], v[210:213], v[48:51]
	v_mfma_f32_16x16x32_bf16 v[36:39], v[178:181], v[218:221], v[36:39]
	v_mfma_f32_16x16x32_bf16 v[28:31], v[186:189], v[218:221], v[28:31]
	s_setprio 0
	s_barrier
	s_add_i32 s73, s73, 2
	s_add_u32 s48, s48, 0x100
	s_addc_u32 s49, s49, 0
	s_add_u32 s71, s71, 0x100
	s_addc_u32 s72, s72, 0

; #define PG8_STAGE(bufoff, gbase, voff) do { _Pragma("unroll") for (int _i = 0; _i < 2; ++_i) \
;         __builtin_amdgcn_global_load_lds((const unsigned*)((const char*)(gbase) + (voff)[_i]), (PG8_LAS unsigned*)(lds + (bufoff) + ldsw + _i * 8192), 16, 0, 0); } while (0)
; #define PG8_LDA(dst, b, h) do { _Pragma("unroll") for (int m = 0; m < 4; ++m) _Pragma("unroll") for (int k = 0; k < 2; ++k) dst[m][k] = *(const PG8_LAS bf16x8*)(lds + PG8_SA(b, h) + aoff + m * 2048 + k * 1024); } while (0)
; #define PG8_LDB(dst, b, h) do { _Pragma("unroll") for (int n = 0; n < 2; ++n) _Pragma("unroll") for (int k = 0; k < 2; ++k) dst[n][k] = *(const PG8_LAS bf16x8*)(lds + PG8_SB(b, h) + boff + n * 2048 + k * 1024); } while (0)
; #define PG8_MMA(ai, bj, At, Bt) do { __builtin_amdgcn_s_setprio(1); _Pragma("unroll") for (int m = 0; m < 4; ++m) _Pragma("unroll") for (int n = 0; n < 2; ++n) _Pragma("unroll") for (int k = 0; k < 2; ++k) \
;         acc[ai][bj][m][n] = __builtin_amdgcn_mfma_f32_16x16x32_bf16(Bt[n][k], At[m][k], acc[ai][bj][m][n], 0, 0, 0); __builtin_amdgcn_s_setprio(0); } while (0)
; template <class Epi, class Sched, bool ALIGN_EPI = false, bool SP2 = false>
; __device__ __forceinline__ void gemm_phase(PG8_LAS unsigned char* lds, const Gemm g, const Sched& S, const Epi& E) {
;     ...
;         const bool has_next = S.next(ui + 1, nxt);
;         const char* nA = has_next ? (const char*)(nxt.seg ? g.A2 : g.A) + (size_t)nxt.pm * tstep : cA; const char* nB = has_next ? (const char*)(nxt.seg ? g.Bt2 : g.Bt) + (size_t)nxt.pn * tstep : cB;
;         for (int t = 0; t < nt; t += 2) {
;             const bool last = (t == nt - 2);
;             const char* a1 = cA + (size_t)(t + 1) * kstep;
;             const char* a2 = last ? nA : cA + (size_t)(t + 2) * kstep; const char* b2 = last ? nB : cB + (size_t)(t + 2) * kstep;
;             const char* a3 = a2 + kstep; const char* b3 = b2 + kstep;
;             if (last && has_next) S.a_ready(nxt);
;             if constexpr (SP2) {
;             PG8_LDB(B0, 0, 0); PG8_LDB(B1, 0, 1); PG8_SCHED; PG8_LDA(At, 0, 0); PG8_STAGE(PG8_SA(1, 1), a1 + hstep, voffA);
;             PG8_WAIT_V(8); PG8_WAIT_L(0); PG8_BAR; PG8_MMA(0, 0, At, B0); PG8_MMA(0, 1, At, B1); PG8_BAR; PG8_SCHED;
;             PG8_LDA(At, 0, 1); PG8_STAGE(PG8_SB(0, 0), b2, voffB); PG8_STAGE(PG8_SB(0, 1), b2 + hstep, voffB); PG8_STAGE(PG8_SA(0, 0), a2, voffA);
.LBB0_749:
	s_ashr_i32 s25, s24, 31
	s_lshl_b64 s[26:27], s[24:25], 20
	s_add_u32 s26, s35, s26
	s_addc_u32 s27, s44, s27
	s_and_b64 s[28:29], s[0:1], exec
	s_cselect_b32 s25, s27, s39
	s_cselect_b32 s62, s26, s38
	s_ashr_i32 s23, s22, 31
	s_lshl_b64 s[28:29], s[22:23], 20
	s_add_u32 s28, s45, s28
	s_addc_u32 s29, s46, s29
	s_and_b64 s[36:37], s[0:1], exec
	s_cselect_b32 s23, s29, s41
	s_cselect_b32 s63, s28, s40
	s_add_u32 s38, s38, 0x80080
	s_addc_u32 s39, s39, 0
	s_add_u32 s64, s40, 0x100
	v_mov_b32_e32 v0, 0
	s_addc_u32 s65, s41, 0
	s_mov_b32 s66, -2
	ds_read_b128 v[154:157], v150
	ds_read_b128 v[160:163], v151
	ds_read_b128 v[164:167], v150 offset:2048
	ds_read_b128 v[168:171], v151 offset:2048
	ds_read_b128 v[172:175], v150 offset:16384
	ds_read_b128 v[176:179], v151 offset:16384
	ds_read_b128 v[180:183], v150 offset:18432
	ds_read_b128 v[184:187], v151 offset:18432
	s_add_u32 s36, s38, 0xfff80080
	s_addc_u32 s37, s39, -1
	s_cmp_eq_u32 s66, 28
	s_cselect_b32 s43, s25, s37
	s_cselect_b32 s42, s62, s36
	s_cselect_b32 s41, s23, s65
	s_cselect_b32 s40, s63, s64
	v_lshl_add_u64 v[146:147], s[38:39], 0, v[136:137]
	s_add_i32 m0, s31, 0xc000
	ds_read_b128 v[188:191], v152
	ds_read_b128 v[192:195], v242
	ds_read_b128 v[196:199], v152 offset:2048
	ds_read_b128 v[200:203], v242 offset:2048
	ds_read_b128 v[204:207], v152 offset:4096
	ds_read_b128 v[208:211], v242 offset:4096
	ds_read_b128 v[212:215], v152 offset:6144
	ds_read_b128 v[216:219], v242 offset:6144
	global_load_lds_dwordx4 v[146:147], off
	v_lshl_add_u64 v[146:147], s[38:39], 0, v[138:139]
	s_add_i32 m0, s31, 0xe000
	s_nop 0
	global_load_lds_dwordx4 v[146:147], off
	s_waitcnt vmcnt(8)
	s_waitcnt lgkmcnt(0)
	s_barrier
	s_setprio 1
	s_waitcnt lgkmcnt(0)
	v_mfma_f32_16x16x32_bf16 v[124:127], v[154:157], v[188:191], 0
	v_mfma_f32_16x16x32_bf16 v[120:123], v[164:167], v[188:191], 0
	v_mfma_f32_16x16x32_bf16 v[116:119], v[154:157], v[196:199], 0
	v_mfma_f32_16x16x32_bf16 v[108:111], v[164:167], v[196:199], 0
	v_mfma_f32_16x16x32_bf16 v[100:103], v[154:157], v[204:207], 0
	v_mfma_f32_16x16x32_bf16 v[92:95], v[164:167], v[204:207], 0
	v_mfma_f32_16x16x32_bf16 v[84:87], v[154:157], v[212:215], 0
	v_mfma_f32_16x16x32_bf16 v[76:79], v[164:167], v[212:215], 0
	v_mfma_f32_16x16x32_bf16 v[124:127], v[160:163], v[192:195], v[124:127]
	v_mfma_f32_16x16x32_bf16 v[120:123], v[168:171], v[192:195], v[120:123]
	v_mfma_f32_16x16x32_bf16 v[116:119], v[160:163], v[200:203], v[116:119]
	v_mfma_f32_16x16x32_bf16 v[108:111], v[168:171], v[200:203], v[108:111]
	v_mfma_f32_16x16x32_bf16 v[100:103], v[160:163], v[208:211], v[100:103]
	v_mfma_f32_16x16x32_bf16 v[92:95], v[168:171], v[208:211], v[92:95]
	v_mfma_f32_16x16x32_bf16 v[84:87], v[160:163], v[216:219], v[84:87]
	v_mfma_f32_16x16x32_bf16 v[76:79], v[168:171], v[216:219], v[76:79]
	s_setprio 0
	s_setprio 1
	v_mfma_f32_16x16x32_bf16 v[112:115], v[172:175], v[188:191], 0
	v_mfma_f32_16x16x32_bf16 v[104:107], v[180:183], v[188:191], 0
	v_mfma_f32_16x16x32_bf16 v[96:99], v[172:175], v[196:199], 0
	v_mfma_f32_16x16x32_bf16 v[88:91], v[180:183], v[196:199], 0
	v_mfma_f32_16x16x32_bf16 v[80:83], v[172:175], v[204:207], 0
	v_mfma_f32_16x16x32_bf16 v[72:75], v[180:183], v[204:207], 0
	v_mfma_f32_16x16x32_bf16 v[68:71], v[172:175], v[212:215], 0
	v_mfma_f32_16x16x32_bf16 v[64:67], v[180:183], v[212:215], 0
	v_mfma_f32_16x16x32_bf16 v[112:115], v[176:179], v[192:195], v[112:115]
	v_mfma_f32_16x16x32_bf16 v[104:107], v[184:187], v[192:195], v[104:107]
	v_mfma_f32_16x16x32_bf16 v[96:99], v[176:179], v[200:203], v[96:99]
	v_mfma_f32_16x16x32_bf16 v[88:91], v[184:187], v[200:203], v[88:91]
	v_mfma_f32_16x16x32_bf16 v[80:83], v[176:179], v[208:211], v[80:83]
	v_mfma_f32_16x16x32_bf16 v[72:75], v[184:187], v[208:211], v[72:75]
	v_mfma_f32_16x16x32_bf16 v[68:71], v[176:179], v[216:219], v[68:71]
	v_mfma_f32_16x16x32_bf16 v[64:67], v[184:187], v[216:219], v[64:67]
	s_setprio 0
	s_barrier
	s_add_i32 s36, s55, s47
	v_lshl_add_u64 v[146:147], s[40:41], 0, v[130:131]
	s_mov_b32 m0, s36
	ds_read_b128 v[188:191], v152 offset:16384
	ds_read_b128 v[192:195], v242 offset:16384
	ds_read_b128 v[196:199], v152 offset:18432
	ds_read_b128 v[200:203], v242 offset:18432
	ds_read_b128 v[204:207], v152 offset:20480
	ds_read_b128 v[208:211], v242 offset:20480
	ds_read_b128 v[212:215], v152 offset:22528
	ds_read_b128 v[216:219], v242 offset:22528
	global_load_lds_dwordx4 v[146:147], off
	s_add_i32 m0, s36, 0x2000
	s_add_u32 s36, s40, 0x80000
	v_lshl_add_u64 v[220:221], s[40:41], 0, v[134:135]
	s_addc_u32 s37, s41, 0
	s_add_i32 s67, s56, s47
	global_load_lds_dwordx4 v[220:221], off
	v_lshl_add_u64 v[222:223], s[36:37], 0, v[130:131]
	s_mov_b32 m0, s67
	v_lshl_add_u64 v[224:225], s[42:43], 0, v[132:133]
	global_load_lds_dwordx4 v[222:223], off
	v_lshl_add_u64 v[222:223], s[36:37], 0, v[134:135]
	s_add_i32 m0, s67, 0x2000
	s_nop 0
	global_load_lds_dwordx4 v[222:223], off
	v_lshl_add_u64 v[222:223], s[42:43], 0, v[128:129]
	s_mov_b32 m0, s31
	s_nop 0
	global_load_lds_dwordx4 v[222:223], off
	s_mov_b32 m0, s48
	s_nop 0
	global_load_lds_dwordx4 v[224:225], off
	s_waitcnt vmcnt(8)
	s_waitcnt lgkmcnt(0)
	s_barrier
; #define PG8_STAGE(bufoff, gbase, voff) do { _Pragma("unroll") for (int _i = 0; _i < 2; ++_i) \
;         __builtin_amdgcn_global_load_lds((const unsigned*)((const char*)(gbase) + (voff)[_i]), (PG8_LAS unsigned*)(lds + (bufoff) + ldsw + _i * 8192), 16, 0, 0); } while (0)
; #define PG8_LDA(dst, b, h) do { _Pragma("unroll") for (int m = 0; m < 4; ++m) _Pragma("unroll") for (int k = 0; k < 2; ++k) dst[m][k] = *(const PG8_LAS bf16x8*)(lds + PG8_SA(b, h) + aoff + m * 2048 + k * 1024); } while (0)
; #define PG8_LDB(dst, b, h) do { _Pragma("unroll") for (int n = 0; n < 2; ++n) _Pragma("unroll") for (int k = 0; k < 2; ++k) dst[n][k] = *(const PG8_LAS bf16x8*)(lds + PG8_SB(b, h) + boff + n * 2048 + k * 1024); } while (0)
; #define PG8_MMA(ai, bj, At, Bt) do { __builtin_amdgcn_s_setprio(1); _Pragma("unroll") for (int m = 0; m < 4; ++m) _Pragma("unroll") for (int n = 0; n < 2; ++n) _Pragma("unroll") for (int k = 0; k < 2; ++k) \
;         acc[ai][bj][m][n] = __builtin_amdgcn_mfma_f32_16x16x32_bf16(Bt[n][k], At[m][k], acc[ai][bj][m][n], 0, 0, 0); __builtin_amdgcn_s_setprio(0); } while (0)
; #define PG8_WAIT_V(n) asm volatile("s_waitcnt vmcnt(" #n ")" ::: "memory")
; #define PG8_WAIT_L(n) asm volatile("s_waitcnt lgkmcnt(" #n ")" ::: "memory")
; #define PG8_BAR __builtin_amdgcn_s_barrier()
; #define PG8_SCHED __builtin_amdgcn_sched_barrier(0)
; template <class Epi, class Sched, bool ALIGN_EPI = false, bool SP2 = false>
; __device__ __forceinline__ void gemm_phase(PG8_LAS unsigned char* lds, const Gemm g, const Sched& S, const Epi& E) {
;     ...
;             PG8_WAIT_V(8); PG8_WAIT_L(0); PG8_BAR; PG8_MMA(1, 0, At, B0); PG8_MMA(1, 1, At, B1); PG8_BAR; PG8_SCHED;
;             PG8_LDB(B0, 1, 0); PG8_LDB(B1, 1, 1); PG8_SCHED; PG8_LDA(At, 1, 0); PG8_STAGE(PG8_SA(0, 1), a2 + hstep, voffA);
;             PG8_WAIT_V(8); PG8_WAIT_L(0); PG8_BAR; PG8_MMA(0, 0, At, B0); PG8_MMA(0, 1, At, B1); PG8_BAR; PG8_SCHED;
	s_setprio 1
	s_waitcnt lgkmcnt(0)
	v_mfma_f32_16x16x32_bf16 v[60:63], v[154:157], v[188:191], 0
	v_mfma_f32_16x16x32_bf16 v[56:59], v[164:167], v[188:191], 0
	v_mfma_f32_16x16x32_bf16 v[52:55], v[154:157], v[196:199], 0
	v_mfma_f32_16x16x32_bf16 v[44:47], v[164:167], v[196:199], 0
	v_mfma_f32_16x16x32_bf16 v[36:39], v[154:157], v[204:207], 0
	v_mfma_f32_16x16x32_bf16 v[28:31], v[164:167], v[204:207], 0
	v_mfma_f32_16x16x32_bf16 v[20:23], v[154:157], v[212:215], 0
	v_mfma_f32_16x16x32_bf16 v[12:15], v[164:167], v[212:215], 0
	v_mfma_f32_16x16x32_bf16 v[60:63], v[160:163], v[192:195], v[60:63]
	v_mfma_f32_16x16x32_bf16 v[56:59], v[168:171], v[192:195], v[56:59]
	v_mfma_f32_16x16x32_bf16 v[52:55], v[160:163], v[200:203], v[52:55]
	v_mfma_f32_16x16x32_bf16 v[44:47], v[168:171], v[200:203], v[44:47]
	v_mfma_f32_16x16x32_bf16 v[36:39], v[160:163], v[208:211], v[36:39]
	v_mfma_f32_16x16x32_bf16 v[28:31], v[168:171], v[208:211], v[28:31]
	v_mfma_f32_16x16x32_bf16 v[20:23], v[160:163], v[216:219], v[20:23]
	v_mfma_f32_16x16x32_bf16 v[12:15], v[168:171], v[216:219], v[12:15]
	s_setprio 0
	s_setprio 1
	v_mfma_f32_16x16x32_bf16 v[48:51], v[172:175], v[188:191], 0
	v_mfma_f32_16x16x32_bf16 v[40:43], v[180:183], v[188:191], 0
	v_mfma_f32_16x16x32_bf16 v[32:35], v[172:175], v[196:199], 0
	v_mfma_f32_16x16x32_bf16 v[24:27], v[180:183], v[196:199], 0
	v_mfma_f32_16x16x32_bf16 v[16:19], v[172:175], v[204:207], 0
	v_mfma_f32_16x16x32_bf16 v[8:11], v[180:183], v[204:207], 0
	v_mfma_f32_16x16x32_bf16 v[4:7], v[172:175], v[212:215], 0
	v_mfma_f32_16x16x32_bf16 v[0:3], v[180:183], v[212:215], 0
	v_mfma_f32_16x16x32_bf16 v[48:51], v[176:179], v[192:195], v[48:51]
	v_mfma_f32_16x16x32_bf16 v[40:43], v[184:187], v[192:195], v[40:43]
	v_mfma_f32_16x16x32_bf16 v[32:35], v[176:179], v[200:203], v[32:35]
	v_mfma_f32_16x16x32_bf16 v[24:27], v[184:187], v[200:203], v[24:27]
	v_mfma_f32_16x16x32_bf16 v[16:19], v[176:179], v[208:211], v[16:19]
	v_mfma_f32_16x16x32_bf16 v[8:11], v[184:187], v[208:211], v[8:11]
	v_mfma_f32_16x16x32_bf16 v[4:7], v[176:179], v[216:219], v[4:7]
	v_mfma_f32_16x16x32_bf16 v[0:3], v[184:187], v[216:219], v[0:3]
	s_setprio 0
	s_barrier
	s_add_i32 s67, 0, 0x18000
	v_add_u32_e32 v153, s67, v148
	s_add_i32 s68, 0, 0x1c000
	ds_read_b128 v[154:157], v150 offset:32768
	ds_read_b128 v[160:163], v151 offset:32768
	ds_read_b128 v[164:167], v150 offset:34816
	ds_read_b128 v[168:171], v151 offset:34816
	v_add_u32_e32 v153, s68, v148
	ds_read_b128 v[172:175], v150 offset:49152
	ds_read_b128 v[176:179], v151 offset:49152
	ds_read_b128 v[180:183], v150 offset:51200
	ds_read_b128 v[184:187], v151 offset:51200
	s_add_u32 s36, s42, 0x80000
	s_addc_u32 s37, s43, 0
	s_mov_b32 m0, s49
	v_lshl_add_u64 v[226:227], s[36:37], 0, v[128:129]
	ds_read_b128 v[188:191], v152 offset:32768
	ds_read_b128 v[192:195], v242 offset:32768
	ds_read_b128 v[196:199], v152 offset:34816
	ds_read_b128 v[200:203], v242 offset:34816
	ds_read_b128 v[204:207], v152 offset:36864
	ds_read_b128 v[208:211], v242 offset:36864
	ds_read_b128 v[212:215], v152 offset:38912
	ds_read_b128 v[216:219], v242 offset:38912
	global_load_lds_dwordx4 v[226:227], off
	v_lshl_add_u64 v[226:227], s[36:37], 0, v[132:133]
	s_mov_b32 m0, s50
	s_nop 0
	global_load_lds_dwordx4 v[226:227], off
	s_waitcnt vmcnt(8)
	s_waitcnt lgkmcnt(0)
	s_barrier
	s_setprio 1
	s_waitcnt lgkmcnt(0)
	v_mfma_f32_16x16x32_bf16 v[124:127], v[154:157], v[188:191], v[124:127]
	v_mfma_f32_16x16x32_bf16 v[120:123], v[164:167], v[188:191], v[120:123]
	v_mfma_f32_16x16x32_bf16 v[116:119], v[154:157], v[196:199], v[116:119]
	v_mfma_f32_16x16x32_bf16 v[108:111], v[164:167], v[196:199], v[108:111]
	v_mfma_f32_16x16x32_bf16 v[100:103], v[154:157], v[204:207], v[100:103]
	v_mfma_f32_16x16x32_bf16 v[92:95], v[164:167], v[204:207], v[92:95]
	v_mfma_f32_16x16x32_bf16 v[84:87], v[154:157], v[212:215], v[84:87]
	v_mfma_f32_16x16x32_bf16 v[76:79], v[164:167], v[212:215], v[76:79]
	v_mfma_f32_16x16x32_bf16 v[124:127], v[160:163], v[192:195], v[124:127]
	v_mfma_f32_16x16x32_bf16 v[120:123], v[168:171], v[192:195], v[120:123]
	v_mfma_f32_16x16x32_bf16 v[116:119], v[160:163], v[200:203], v[116:119]
	v_mfma_f32_16x16x32_bf16 v[108:111], v[168:171], v[200:203], v[108:111]
	v_mfma_f32_16x16x32_bf16 v[100:103], v[160:163], v[208:211], v[100:103]
	v_mfma_f32_16x16x32_bf16 v[92:95], v[168:171], v[208:211], v[92:95]
	v_mfma_f32_16x16x32_bf16 v[84:87], v[160:163], v[216:219], v[84:87]
	v_mfma_f32_16x16x32_bf16 v[76:79], v[168:171], v[216:219], v[76:79]
	s_setprio 0
	s_setprio 1
	v_mfma_f32_16x16x32_bf16 v[112:115], v[172:175], v[188:191], v[112:115]
	v_mfma_f32_16x16x32_bf16 v[104:107], v[180:183], v[188:191], v[104:107]
	v_mfma_f32_16x16x32_bf16 v[96:99], v[172:175], v[196:199], v[96:99]
	v_mfma_f32_16x16x32_bf16 v[88:91], v[180:183], v[196:199], v[88:91]
	v_mfma_f32_16x16x32_bf16 v[80:83], v[172:175], v[204:207], v[80:83]
	v_mfma_f32_16x16x32_bf16 v[72:75], v[180:183], v[204:207], v[72:75]
	v_mfma_f32_16x16x32_bf16 v[68:71], v[172:175], v[212:215], v[68:71]
	v_mfma_f32_16x16x32_bf16 v[64:67], v[180:183], v[212:215], v[64:67]
	v_mfma_f32_16x16x32_bf16 v[112:115], v[176:179], v[192:195], v[112:115]
	v_mfma_f32_16x16x32_bf16 v[104:107], v[184:187], v[192:195], v[104:107]
	v_mfma_f32_16x16x32_bf16 v[96:99], v[176:179], v[200:203], v[96:99]
	v_mfma_f32_16x16x32_bf16 v[88:91], v[184:187], v[200:203], v[88:91]
	v_mfma_f32_16x16x32_bf16 v[80:83], v[176:179], v[208:211], v[80:83]
	v_mfma_f32_16x16x32_bf16 v[72:75], v[184:187], v[208:211], v[72:75]
	v_mfma_f32_16x16x32_bf16 v[68:71], v[176:179], v[216:219], v[68:71]
	v_mfma_f32_16x16x32_bf16 v[64:67], v[184:187], v[216:219], v[64:67]
	s_setprio 0
	s_barrier
; #define PG8_STAGE(bufoff, gbase, voff) do { _Pragma("unroll") for (int _i = 0; _i < 2; ++_i) \
;         __builtin_amdgcn_global_load_lds((const unsigned*)((const char*)(gbase) + (voff)[_i]), (PG8_LAS unsigned*)(lds + (bufoff) + ldsw + _i * 8192), 16, 0, 0); } while (0)
; #define PG8_LDA(dst, b, h) do { _Pragma("unroll") for (int m = 0; m < 4; ++m) _Pragma("unroll") for (int k = 0; k < 2; ++k) dst[m][k] = *(const PG8_LAS bf16x8*)(lds + PG8_SA(b, h) + aoff + m * 2048 + k * 1024); } while (0)
; #define PG8_MMA(ai, bj, At, Bt) do { __builtin_amdgcn_s_setprio(1); _Pragma("unroll") for (int m = 0; m < 4; ++m) _Pragma("unroll") for (int n = 0; n < 2; ++n) _Pragma("unroll") for (int k = 0; k < 2; ++k) \
;         acc[ai][bj][m][n] = __builtin_amdgcn_mfma_f32_16x16x32_bf16(Bt[n][k], At[m][k], acc[ai][bj][m][n], 0, 0, 0); __builtin_amdgcn_s_setprio(0); } while (0)
; #define PG8_WAIT_V(n) asm volatile("s_waitcnt vmcnt(" #n ")" ::: "memory")
; #define PG8_WAIT_L(n) asm volatile("s_waitcnt lgkmcnt(" #n ")" ::: "memory")
; #define PG8_BAR __builtin_amdgcn_s_barrier()
; #define PG8_SCHED __builtin_amdgcn_sched_barrier(0)
; template <class Epi, class Sched, bool ALIGN_EPI = false, bool SP2 = false>
; __device__ __forceinline__ void gemm_phase(PG8_LAS unsigned char* lds, const Gemm g, const Sched& S, const Epi& E) {
;     ...
;         for (int t = 0; t < nt; t += 2) {
;     ...
;             PG8_LDA(At, 1, 1); PG8_STAGE(PG8_SB(1, 0), b3, voffB); PG8_STAGE(PG8_SB(1, 1), b3 + hstep, voffB); PG8_STAGE(PG8_SA(1, 0), a3, voffA);
;             PG8_WAIT_V(8); PG8_WAIT_L(0); PG8_BAR; PG8_MMA(1, 0, At, B0); PG8_MMA(1, 1, At, B1); PG8_BAR; PG8_SCHED;
	s_add_i32 s36, s67, s47
	v_lshl_add_u64 v[146:147], v[146:147], 0, s[10:11]
	s_mov_b32 m0, s36
	ds_read_b128 v[188:191], v152 offset:49152
	ds_read_b128 v[192:195], v242 offset:49152
	ds_read_b128 v[196:199], v152 offset:51200
	ds_read_b128 v[200:203], v242 offset:51200
	ds_read_b128 v[204:207], v152 offset:53248
	ds_read_b128 v[208:211], v242 offset:53248
	ds_read_b128 v[212:215], v152 offset:55296
	ds_read_b128 v[216:219], v242 offset:55296
	global_load_lds_dwordx4 v[146:147], off
	s_add_i32 m0, s36, 0x2000
	s_add_u32 s36, s40, 0x80080
	v_lshl_add_u64 v[146:147], v[220:221], 0, s[10:11]
	s_addc_u32 s37, s41, 0
	s_add_i32 s40, s68, s47
	global_load_lds_dwordx4 v[146:147], off
	v_lshl_add_u64 v[146:147], s[36:37], 0, v[130:131]
	s_mov_b32 m0, s40
	s_nop 0
	global_load_lds_dwordx4 v[146:147], off
	v_lshl_add_u64 v[146:147], s[36:37], 0, v[134:135]
	s_add_i32 m0, s40, 0x2000
	s_nop 0
	global_load_lds_dwordx4 v[146:147], off
	v_lshl_add_u64 v[146:147], v[222:223], 0, s[10:11]
	s_mov_b32 m0, s52
	s_nop 0
	global_load_lds_dwordx4 v[146:147], off
	v_lshl_add_u64 v[146:147], v[224:225], 0, s[10:11]
	s_mov_b32 m0, s53
	s_nop 0
	global_load_lds_dwordx4 v[146:147], off
	s_waitcnt vmcnt(8)
	s_waitcnt lgkmcnt(0)
	s_barrier
	s_setprio 1
	s_waitcnt lgkmcnt(0)
	v_mfma_f32_16x16x32_bf16 v[60:63], v[154:157], v[188:191], v[60:63]
	v_mfma_f32_16x16x32_bf16 v[56:59], v[164:167], v[188:191], v[56:59]
	v_mfma_f32_16x16x32_bf16 v[52:55], v[154:157], v[196:199], v[52:55]
	v_mfma_f32_16x16x32_bf16 v[44:47], v[164:167], v[196:199], v[44:47]
	v_mfma_f32_16x16x32_bf16 v[36:39], v[154:157], v[204:207], v[36:39]
	v_mfma_f32_16x16x32_bf16 v[28:31], v[164:167], v[204:207], v[28:31]
	v_mfma_f32_16x16x32_bf16 v[20:23], v[154:157], v[212:215], v[20:23]
	v_mfma_f32_16x16x32_bf16 v[12:15], v[164:167], v[212:215], v[12:15]
	v_mfma_f32_16x16x32_bf16 v[60:63], v[160:163], v[192:195], v[60:63]
	v_mfma_f32_16x16x32_bf16 v[56:59], v[168:171], v[192:195], v[56:59]
	v_mfma_f32_16x16x32_bf16 v[52:55], v[160:163], v[200:203], v[52:55]
	v_mfma_f32_16x16x32_bf16 v[44:47], v[168:171], v[200:203], v[44:47]
	v_mfma_f32_16x16x32_bf16 v[36:39], v[160:163], v[208:211], v[36:39]
	v_mfma_f32_16x16x32_bf16 v[28:31], v[168:171], v[208:211], v[28:31]
	v_mfma_f32_16x16x32_bf16 v[20:23], v[160:163], v[216:219], v[20:23]
	v_mfma_f32_16x16x32_bf16 v[12:15], v[168:171], v[216:219], v[12:15]
	s_setprio 0
	s_setprio 1
	v_mfma_f32_16x16x32_bf16 v[48:51], v[172:175], v[188:191], v[48:51]
	v_mfma_f32_16x16x32_bf16 v[40:43], v[180:183], v[188:191], v[40:43]
	v_mfma_f32_16x16x32_bf16 v[32:35], v[172:175], v[196:199], v[32:35]
	v_mfma_f32_16x16x32_bf16 v[24:27], v[180:183], v[196:199], v[24:27]
	v_mfma_f32_16x16x32_bf16 v[16:19], v[172:175], v[204:207], v[16:19]
	v_mfma_f32_16x16x32_bf16 v[8:11], v[180:183], v[204:207], v[8:11]
	v_mfma_f32_16x16x32_bf16 v[4:7], v[172:175], v[212:215], v[4:7]
	v_mfma_f32_16x16x32_bf16 v[0:3], v[180:183], v[212:215], v[0:3]
	v_mfma_f32_16x16x32_bf16 v[48:51], v[176:179], v[192:195], v[48:51]
	v_mfma_f32_16x16x32_bf16 v[40:43], v[184:187], v[192:195], v[40:43]
	v_mfma_f32_16x16x32_bf16 v[32:35], v[176:179], v[200:203], v[32:35]
	v_mfma_f32_16x16x32_bf16 v[24:27], v[184:187], v[200:203], v[24:27]
	v_mfma_f32_16x16x32_bf16 v[16:19], v[176:179], v[208:211], v[16:19]
	v_mfma_f32_16x16x32_bf16 v[8:11], v[184:187], v[208:211], v[8:11]
	v_mfma_f32_16x16x32_bf16 v[4:7], v[176:179], v[216:219], v[4:7]
	v_mfma_f32_16x16x32_bf16 v[0:3], v[184:187], v[216:219], v[0:3]
	s_setprio 0
	s_barrier
	s_add_i32 s66, s66, 2
	s_add_u32 s38, s38, 0x100
	s_addc_u32 s39, s39, 0
	s_add_u32 s64, s64, 0x100
	s_addc_u32 s65, s65, 0

; #define PG8_STAGE(bufoff, gbase, voff) do { _Pragma("unroll") for (int _i = 0; _i < 2; ++_i) \
;         __builtin_amdgcn_global_load_lds((const unsigned*)((const char*)(gbase) + (voff)[_i]), (PG8_LAS unsigned*)(lds + (bufoff) + ldsw + _i * 8192), 16, 0, 0); } while (0)
; #define PG8_LDA(dst, b, h) do { _Pragma("unroll") for (int m = 0; m < 4; ++m) _Pragma("unroll") for (int k = 0; k < 2; ++k) dst[m][k] = *(const PG8_LAS bf16x8*)(lds + PG8_SA(b, h) + aoff + m * 2048 + k * 1024); } while (0)
; #define PG8_LDB(dst, b, h) do { _Pragma("unroll") for (int n = 0; n < 2; ++n) _Pragma("unroll") for (int k = 0; k < 2; ++k) dst[n][k] = *(const PG8_LAS bf16x8*)(lds + PG8_SB(b, h) + boff + n * 2048 + k * 1024); } while (0)
; #define PG8_MMA(ai, bj, At, Bt) do { __builtin_amdgcn_s_setprio(1); _Pragma("unroll") for (int m = 0; m < 4; ++m) _Pragma("unroll") for (int n = 0; n < 2; ++n) _Pragma("unroll") for (int k = 0; k < 2; ++k) \
;         acc[ai][bj][m][n] = __builtin_amdgcn_mfma_f32_16x16x32_bf16(Bt[n][k], At[m][k], acc[ai][bj][m][n], 0, 0, 0); __builtin_amdgcn_s_setprio(0); } while (0)
; template <class Epi, class Sched, bool ALIGN_EPI = false, bool SP2 = false>
; __device__ __forceinline__ void gemm_phase(PG8_LAS unsigned char* lds, const Gemm g, const Sched& S, const Epi& E) {
;     ...
;         const bool has_next = S.next(ui + 1, nxt);
;         const char* nA = has_next ? (const char*)(nxt.seg ? g.A2 : g.A) + (size_t)nxt.pm * tstep : cA; const char* nB = has_next ? (const char*)(nxt.seg ? g.Bt2 : g.Bt) + (size_t)nxt.pn * tstep : cB;
;         for (int t = 0; t < nt; t += 2) {
;             const bool last = (t == nt - 2);
;             const char* a1 = cA + (size_t)(t + 1) * kstep;
;             const char* a2 = last ? nA : cA + (size_t)(t + 2) * kstep; const char* b2 = last ? nB : cB + (size_t)(t + 2) * kstep;
;             const char* a3 = a2 + kstep; const char* b3 = b2 + kstep;
;             if (last && has_next) S.a_ready(nxt);
;             if constexpr (SP2) {
;             PG8_LDB(B0, 0, 0); PG8_LDB(B1, 0, 1); PG8_SCHED; PG8_LDA(At, 0, 0); PG8_STAGE(PG8_SA(1, 1), a1 + hstep, voffA);
;             PG8_WAIT_V(8); PG8_WAIT_L(0); PG8_BAR; PG8_MMA(0, 0, At, B0); PG8_MMA(0, 1, At, B1); PG8_BAR; PG8_SCHED;
;             PG8_LDA(At, 0, 1); PG8_STAGE(PG8_SB(0, 0), b2, voffB); PG8_STAGE(PG8_SB(0, 1), b2 + hstep, voffB); PG8_STAGE(PG8_SA(0, 0), a2, voffA);
.LBB0_881:
	s_ashr_i32 s49, s48, 31
	s_lshl_b64 s[36:37], s[48:49], 20
	s_add_u32 s50, s33, s36
	s_addc_u32 s51, s35, s37
	s_and_b64 s[36:37], s[12:13], exec
	s_cselect_b32 s15, s51, s19
	s_cselect_b32 s17, s50, s18
	s_ashr_i32 s47, s46, 31
	s_lshl_b64 s[36:37], s[46:47], 20
	s_add_u32 s52, s56, s36
	s_addc_u32 s53, s57, s37
	s_and_b64 s[36:37], s[12:13], exec
	s_cselect_b32 s47, s53, s21
	s_cselect_b32 s49, s52, s20
	s_add_u32 s18, s18, 0x80080
	s_addc_u32 s19, s19, 0
	s_add_u32 s76, s20, 0x100
	v_mov_b32_e32 v120, 0
	s_addc_u32 s77, s21, 0
	s_mov_b32 s78, -2
	ds_read_b128 v[128:131], v187
	ds_read_b128 v[132:135], v188
	ds_read_b128 v[136:139], v187 offset:2048
	ds_read_b128 v[140:143], v188 offset:2048
	ds_read_b128 v[168:171], v187 offset:16384
	ds_read_b128 v[172:175], v188 offset:16384
	ds_read_b128 v[176:179], v187 offset:18432
	ds_read_b128 v[194:197], v188 offset:18432
	s_add_u32 s20, s18, 0xfff80080
	s_addc_u32 s21, s19, -1
	s_cmp_eq_u32 s78, 28
	s_cselect_b32 s55, s15, s21
	s_cselect_b32 s54, s17, s20
	s_cselect_b32 s21, s47, s77
	s_cselect_b32 s20, s49, s76
	v_lshl_add_u64 v[180:181], s[18:19], 0, v[160:161]
	s_add_i32 m0, s60, 0xc000
	ds_read_b128 v[198:201], v189
	ds_read_b128 v[202:205], v242
	ds_read_b128 v[206:209], v189 offset:2048
	ds_read_b128 v[210:213], v242 offset:2048
	ds_read_b128 v[214:217], v189 offset:4096
	ds_read_b128 v[218:221], v242 offset:4096
	ds_read_b128 v[222:225], v189 offset:6144
	ds_read_b128 v[226:229], v242 offset:6144
	global_load_lds_dwordx4 v[180:181], off
	v_lshl_add_u64 v[180:181], s[18:19], 0, v[162:163]
	s_add_i32 m0, s60, 0xe000
	s_nop 0
	global_load_lds_dwordx4 v[180:181], off
	s_waitcnt vmcnt(8)
	s_waitcnt lgkmcnt(0)
	s_barrier
	s_setprio 1
	s_waitcnt lgkmcnt(0)
	v_mfma_f32_16x16x32_bf16 v[120:123], v[128:131], v[198:201], 0
	v_mfma_f32_16x16x32_bf16 v[88:91], v[136:139], v[198:201], 0
	v_mfma_f32_16x16x32_bf16 v[116:119], v[128:131], v[206:209], 0
	v_mfma_f32_16x16x32_bf16 v[84:87], v[136:139], v[206:209], 0
	v_mfma_f32_16x16x32_bf16 v[112:115], v[128:131], v[214:217], 0
	v_mfma_f32_16x16x32_bf16 v[80:83], v[136:139], v[214:217], 0
	v_mfma_f32_16x16x32_bf16 v[100:103], v[128:131], v[222:225], 0
	v_mfma_f32_16x16x32_bf16 v[68:71], v[136:139], v[222:225], 0
	v_mfma_f32_16x16x32_bf16 v[120:123], v[132:135], v[202:205], v[120:123]
	v_mfma_f32_16x16x32_bf16 v[88:91], v[140:143], v[202:205], v[88:91]
	v_mfma_f32_16x16x32_bf16 v[116:119], v[132:135], v[210:213], v[116:119]
	v_mfma_f32_16x16x32_bf16 v[84:87], v[140:143], v[210:213], v[84:87]
	v_mfma_f32_16x16x32_bf16 v[112:115], v[132:135], v[218:221], v[112:115]
	v_mfma_f32_16x16x32_bf16 v[80:83], v[140:143], v[218:221], v[80:83]
	v_mfma_f32_16x16x32_bf16 v[100:103], v[132:135], v[226:229], v[100:103]
	v_mfma_f32_16x16x32_bf16 v[68:71], v[140:143], v[226:229], v[68:71]
	s_setprio 0
	s_setprio 1
	v_mfma_f32_16x16x32_bf16 v[124:127], v[168:171], v[198:201], 0
	v_mfma_f32_16x16x32_bf16 v[92:95], v[176:179], v[198:201], 0
	v_mfma_f32_16x16x32_bf16 v[108:111], v[168:171], v[206:209], 0
	v_mfma_f32_16x16x32_bf16 v[76:79], v[176:179], v[206:209], 0
	v_mfma_f32_16x16x32_bf16 v[104:107], v[168:171], v[214:217], 0
	v_mfma_f32_16x16x32_bf16 v[72:75], v[176:179], v[214:217], 0
	v_mfma_f32_16x16x32_bf16 v[96:99], v[168:171], v[222:225], 0
	v_mfma_f32_16x16x32_bf16 v[64:67], v[176:179], v[222:225], 0
	v_mfma_f32_16x16x32_bf16 v[124:127], v[172:175], v[202:205], v[124:127]
	v_mfma_f32_16x16x32_bf16 v[92:95], v[194:197], v[202:205], v[92:95]
	v_mfma_f32_16x16x32_bf16 v[108:111], v[172:175], v[210:213], v[108:111]
	v_mfma_f32_16x16x32_bf16 v[76:79], v[194:197], v[210:213], v[76:79]
	v_mfma_f32_16x16x32_bf16 v[104:107], v[172:175], v[218:221], v[104:107]
	v_mfma_f32_16x16x32_bf16 v[72:75], v[194:197], v[218:221], v[72:75]
	v_mfma_f32_16x16x32_bf16 v[96:99], v[172:175], v[226:229], v[96:99]
	v_mfma_f32_16x16x32_bf16 v[64:67], v[194:197], v[226:229], v[64:67]
	s_setprio 0
	s_barrier
	s_add_i32 s36, s72, s59
	v_lshl_add_u64 v[180:181], s[20:21], 0, v[148:149]
	s_mov_b32 m0, s36
	ds_read_b128 v[198:201], v189 offset:16384
	ds_read_b128 v[202:205], v242 offset:16384
	ds_read_b128 v[206:209], v189 offset:18432
	ds_read_b128 v[210:213], v242 offset:18432
	ds_read_b128 v[214:217], v189 offset:20480
	ds_read_b128 v[218:221], v242 offset:20480
	ds_read_b128 v[222:225], v189 offset:22528
	ds_read_b128 v[226:229], v242 offset:22528
	global_load_lds_dwordx4 v[180:181], off
	s_add_i32 m0, s36, 0x2000
	s_add_u32 s36, s20, 0x80000
	v_lshl_add_u64 v[230:231], s[20:21], 0, v[152:153]
	s_addc_u32 s37, s21, 0
	s_add_i32 s79, s73, s59
	global_load_lds_dwordx4 v[230:231], off
	v_lshl_add_u64 v[232:233], s[36:37], 0, v[148:149]
	s_mov_b32 m0, s79
	v_lshl_add_u64 v[234:235], s[54:55], 0, v[150:151]
	global_load_lds_dwordx4 v[232:233], off
	v_lshl_add_u64 v[232:233], s[36:37], 0, v[152:153]
	s_add_i32 m0, s79, 0x2000
	s_nop 0
	global_load_lds_dwordx4 v[232:233], off
	v_lshl_add_u64 v[232:233], s[54:55], 0, v[146:147]
	s_mov_b32 m0, s60
	s_nop 0
	global_load_lds_dwordx4 v[232:233], off
	s_mov_b32 m0, s61
	s_nop 0
	global_load_lds_dwordx4 v[234:235], off
	s_waitcnt vmcnt(8)
	s_waitcnt lgkmcnt(0)
	s_barrier
; #define PG8_STAGE(bufoff, gbase, voff) do { _Pragma("unroll") for (int _i = 0; _i < 2; ++_i) \
;         __builtin_amdgcn_global_load_lds((const unsigned*)((const char*)(gbase) + (voff)[_i]), (PG8_LAS unsigned*)(lds + (bufoff) + ldsw + _i * 8192), 16, 0, 0); } while (0)
; #define PG8_LDA(dst, b, h) do { _Pragma("unroll") for (int m = 0; m < 4; ++m) _Pragma("unroll") for (int k = 0; k < 2; ++k) dst[m][k] = *(const PG8_LAS bf16x8*)(lds + PG8_SA(b, h) + aoff + m * 2048 + k * 1024); } while (0)
; #define PG8_LDB(dst, b, h) do { _Pragma("unroll") for (int n = 0; n < 2; ++n) _Pragma("unroll") for (int k = 0; k < 2; ++k) dst[n][k] = *(const PG8_LAS bf16x8*)(lds + PG8_SB(b, h) + boff + n * 2048 + k * 1024); } while (0)
; #define PG8_MMA(ai, bj, At, Bt) do { __builtin_amdgcn_s_setprio(1); _Pragma("unroll") for (int m = 0; m < 4; ++m) _Pragma("unroll") for (int n = 0; n < 2; ++n) _Pragma("unroll") for (int k = 0; k < 2; ++k) \
;         acc[ai][bj][m][n] = __builtin_amdgcn_mfma_f32_16x16x32_bf16(Bt[n][k], At[m][k], acc[ai][bj][m][n], 0, 0, 0); __builtin_amdgcn_s_setprio(0); } while (0)
; #define PG8_WAIT_V(n) asm volatile("s_waitcnt vmcnt(" #n ")" ::: "memory")
; #define PG8_WAIT_L(n) asm volatile("s_waitcnt lgkmcnt(" #n ")" ::: "memory")
; #define PG8_BAR __builtin_amdgcn_s_barrier()
; #define PG8_SCHED __builtin_amdgcn_sched_barrier(0)
; template <class Epi, class Sched, bool ALIGN_EPI = false, bool SP2 = false>
; __device__ __forceinline__ void gemm_phase(PG8_LAS unsigned char* lds, const Gemm g, const Sched& S, const Epi& E) {
;     ...
;             PG8_WAIT_V(8); PG8_WAIT_L(0); PG8_BAR; PG8_MMA(1, 0, At, B0); PG8_MMA(1, 1, At, B1); PG8_BAR; PG8_SCHED;
;             PG8_LDB(B0, 1, 0); PG8_LDB(B1, 1, 1); PG8_SCHED; PG8_LDA(At, 1, 0); PG8_STAGE(PG8_SA(0, 1), a2 + hstep, voffA);
;             PG8_WAIT_V(8); PG8_WAIT_L(0); PG8_BAR; PG8_MMA(0, 0, At, B0); PG8_MMA(0, 1, At, B1); PG8_BAR; PG8_SCHED;
	s_setprio 1
	s_waitcnt lgkmcnt(0)
	v_mfma_f32_16x16x32_bf16 v[60:63], v[128:131], v[198:201], 0
	v_mfma_f32_16x16x32_bf16 v[28:31], v[136:139], v[198:201], 0
	v_mfma_f32_16x16x32_bf16 v[52:55], v[128:131], v[206:209], 0
	v_mfma_f32_16x16x32_bf16 v[20:23], v[136:139], v[206:209], 0
	v_mfma_f32_16x16x32_bf16 v[48:51], v[128:131], v[214:217], 0
	v_mfma_f32_16x16x32_bf16 v[16:19], v[136:139], v[214:217], 0
	v_mfma_f32_16x16x32_bf16 v[44:47], v[128:131], v[222:225], 0
	v_mfma_f32_16x16x32_bf16 v[8:11], v[136:139], v[222:225], 0
	v_mfma_f32_16x16x32_bf16 v[60:63], v[132:135], v[202:205], v[60:63]
	v_mfma_f32_16x16x32_bf16 v[28:31], v[140:143], v[202:205], v[28:31]
	v_mfma_f32_16x16x32_bf16 v[52:55], v[132:135], v[210:213], v[52:55]
	v_mfma_f32_16x16x32_bf16 v[20:23], v[140:143], v[210:213], v[20:23]
	v_mfma_f32_16x16x32_bf16 v[48:51], v[132:135], v[218:221], v[48:51]
	v_mfma_f32_16x16x32_bf16 v[16:19], v[140:143], v[218:221], v[16:19]
	v_mfma_f32_16x16x32_bf16 v[44:47], v[132:135], v[226:229], v[44:47]
	v_mfma_f32_16x16x32_bf16 v[8:11], v[140:143], v[226:229], v[8:11]
	s_setprio 0
	s_setprio 1
	v_mfma_f32_16x16x32_bf16 v[56:59], v[168:171], v[198:201], 0
	v_mfma_f32_16x16x32_bf16 v[24:27], v[176:179], v[198:201], 0
	v_mfma_f32_16x16x32_bf16 v[40:43], v[168:171], v[206:209], 0
	v_mfma_f32_16x16x32_bf16 v[12:15], v[176:179], v[206:209], 0
	v_mfma_f32_16x16x32_bf16 v[36:39], v[168:171], v[214:217], 0
	v_mfma_f32_16x16x32_bf16 v[4:7], v[176:179], v[214:217], 0
	v_mfma_f32_16x16x32_bf16 v[32:35], v[168:171], v[222:225], 0
	v_mfma_f32_16x16x32_bf16 v[0:3], v[176:179], v[222:225], 0
	v_mfma_f32_16x16x32_bf16 v[56:59], v[172:175], v[202:205], v[56:59]
	v_mfma_f32_16x16x32_bf16 v[24:27], v[194:197], v[202:205], v[24:27]
	v_mfma_f32_16x16x32_bf16 v[40:43], v[172:175], v[210:213], v[40:43]
	v_mfma_f32_16x16x32_bf16 v[12:15], v[194:197], v[210:213], v[12:15]
	v_mfma_f32_16x16x32_bf16 v[36:39], v[172:175], v[218:221], v[36:39]
	v_mfma_f32_16x16x32_bf16 v[4:7], v[194:197], v[218:221], v[4:7]
	v_mfma_f32_16x16x32_bf16 v[32:35], v[172:175], v[226:229], v[32:35]
	v_mfma_f32_16x16x32_bf16 v[0:3], v[194:197], v[226:229], v[0:3]
	s_setprio 0
	s_barrier
	s_add_i32 s79, 0, 0x18000
	s_add_i32 s80, 0, 0x1c000
	v_add_u32_e32 v140, s79, v182
	v_add_u32_e32 v154, s80, v182
	ds_read_b128 v[128:131], v187 offset:32768
	ds_read_b128 v[132:135], v188 offset:32768
	ds_read_b128 v[136:139], v187 offset:34816
	ds_read_b128 v[140:143], v188 offset:34816
	ds_read_b128 v[168:171], v187 offset:49152
	ds_read_b128 v[172:175], v188 offset:49152
	ds_read_b128 v[176:179], v187 offset:51200
	ds_read_b128 v[194:197], v188 offset:51200
	s_add_u32 s36, s54, 0x80000
	s_addc_u32 s37, s55, 0
	s_mov_b32 m0, s62
	v_lshl_add_u64 v[236:237], s[36:37], 0, v[146:147]
	ds_read_b128 v[198:201], v189 offset:32768
	ds_read_b128 v[202:205], v242 offset:32768
	ds_read_b128 v[206:209], v189 offset:34816
	ds_read_b128 v[210:213], v242 offset:34816
	ds_read_b128 v[214:217], v189 offset:36864
	ds_read_b128 v[218:221], v242 offset:36864
	ds_read_b128 v[222:225], v189 offset:38912
	ds_read_b128 v[226:229], v242 offset:38912
	global_load_lds_dwordx4 v[236:237], off
	v_lshl_add_u64 v[236:237], s[36:37], 0, v[150:151]
	s_mov_b32 m0, s63
	s_nop 0
	global_load_lds_dwordx4 v[236:237], off
	s_waitcnt vmcnt(8)
	s_waitcnt lgkmcnt(0)
	s_barrier
	s_setprio 1
	s_waitcnt lgkmcnt(0)
	v_mfma_f32_16x16x32_bf16 v[120:123], v[128:131], v[198:201], v[120:123]
	v_mfma_f32_16x16x32_bf16 v[88:91], v[136:139], v[198:201], v[88:91]
	v_mfma_f32_16x16x32_bf16 v[116:119], v[128:131], v[206:209], v[116:119]
	v_mfma_f32_16x16x32_bf16 v[84:87], v[136:139], v[206:209], v[84:87]
	v_mfma_f32_16x16x32_bf16 v[112:115], v[128:131], v[214:217], v[112:115]
	v_mfma_f32_16x16x32_bf16 v[80:83], v[136:139], v[214:217], v[80:83]
	v_mfma_f32_16x16x32_bf16 v[100:103], v[128:131], v[222:225], v[100:103]
	v_mfma_f32_16x16x32_bf16 v[68:71], v[136:139], v[222:225], v[68:71]
	v_mfma_f32_16x16x32_bf16 v[120:123], v[132:135], v[202:205], v[120:123]
	v_mfma_f32_16x16x32_bf16 v[88:91], v[140:143], v[202:205], v[88:91]
	v_mfma_f32_16x16x32_bf16 v[116:119], v[132:135], v[210:213], v[116:119]
	v_mfma_f32_16x16x32_bf16 v[84:87], v[140:143], v[210:213], v[84:87]
	v_mfma_f32_16x16x32_bf16 v[112:115], v[132:135], v[218:221], v[112:115]
	v_mfma_f32_16x16x32_bf16 v[80:83], v[140:143], v[218:221], v[80:83]
	v_mfma_f32_16x16x32_bf16 v[100:103], v[132:135], v[226:229], v[100:103]
	v_mfma_f32_16x16x32_bf16 v[68:71], v[140:143], v[226:229], v[68:71]
	s_setprio 0
	s_setprio 1
	v_mfma_f32_16x16x32_bf16 v[124:127], v[168:171], v[198:201], v[124:127]
	v_mfma_f32_16x16x32_bf16 v[92:95], v[176:179], v[198:201], v[92:95]
	v_mfma_f32_16x16x32_bf16 v[108:111], v[168:171], v[206:209], v[108:111]
	v_mfma_f32_16x16x32_bf16 v[76:79], v[176:179], v[206:209], v[76:79]
	v_mfma_f32_16x16x32_bf16 v[104:107], v[168:171], v[214:217], v[104:107]
	v_mfma_f32_16x16x32_bf16 v[72:75], v[176:179], v[214:217], v[72:75]
	v_mfma_f32_16x16x32_bf16 v[96:99], v[168:171], v[222:225], v[96:99]
	v_mfma_f32_16x16x32_bf16 v[64:67], v[176:179], v[222:225], v[64:67]
	v_mfma_f32_16x16x32_bf16 v[124:127], v[172:175], v[202:205], v[124:127]
	v_mfma_f32_16x16x32_bf16 v[92:95], v[194:197], v[202:205], v[92:95]
	v_mfma_f32_16x16x32_bf16 v[108:111], v[172:175], v[210:213], v[108:111]
	v_mfma_f32_16x16x32_bf16 v[76:79], v[194:197], v[210:213], v[76:79]
	v_mfma_f32_16x16x32_bf16 v[104:107], v[172:175], v[218:221], v[104:107]
	v_mfma_f32_16x16x32_bf16 v[72:75], v[194:197], v[218:221], v[72:75]
	v_mfma_f32_16x16x32_bf16 v[96:99], v[172:175], v[226:229], v[96:99]
	v_mfma_f32_16x16x32_bf16 v[64:67], v[194:197], v[226:229], v[64:67]
	s_setprio 0
	s_barrier
; #define PG8_STAGE(bufoff, gbase, voff) do { _Pragma("unroll") for (int _i = 0; _i < 2; ++_i) \
;         __builtin_amdgcn_global_load_lds((const unsigned*)((const char*)(gbase) + (voff)[_i]), (PG8_LAS unsigned*)(lds + (bufoff) + ldsw + _i * 8192), 16, 0, 0); } while (0)
; #define PG8_LDA(dst, b, h) do { _Pragma("unroll") for (int m = 0; m < 4; ++m) _Pragma("unroll") for (int k = 0; k < 2; ++k) dst[m][k] = *(const PG8_LAS bf16x8*)(lds + PG8_SA(b, h) + aoff + m * 2048 + k * 1024); } while (0)
; #define PG8_MMA(ai, bj, At, Bt) do { __builtin_amdgcn_s_setprio(1); _Pragma("unroll") for (int m = 0; m < 4; ++m) _Pragma("unroll") for (int n = 0; n < 2; ++n) _Pragma("unroll") for (int k = 0; k < 2; ++k) \
;         acc[ai][bj][m][n] = __builtin_amdgcn_mfma_f32_16x16x32_bf16(Bt[n][k], At[m][k], acc[ai][bj][m][n], 0, 0, 0); __builtin_amdgcn_s_setprio(0); } while (0)
; #define PG8_WAIT_V(n) asm volatile("s_waitcnt vmcnt(" #n ")" ::: "memory")
; #define PG8_WAIT_L(n) asm volatile("s_waitcnt lgkmcnt(" #n ")" ::: "memory")
; #define PG8_BAR __builtin_amdgcn_s_barrier()
; #define PG8_SCHED __builtin_amdgcn_sched_barrier(0)
; template <class Epi, class Sched, bool ALIGN_EPI = false, bool SP2 = false>
; __device__ __forceinline__ void gemm_phase(PG8_LAS unsigned char* lds, const Gemm g, const Sched& S, const Epi& E) {
;     ...
;         for (int t = 0; t < nt; t += 2) {
;     ...
;             PG8_LDA(At, 1, 1); PG8_STAGE(PG8_SB(1, 0), b3, voffB); PG8_STAGE(PG8_SB(1, 1), b3 + hstep, voffB); PG8_STAGE(PG8_SA(1, 0), a3, voffA);
;             PG8_WAIT_V(8); PG8_WAIT_L(0); PG8_BAR; PG8_MMA(1, 0, At, B0); PG8_MMA(1, 1, At, B1); PG8_BAR; PG8_SCHED;
	s_add_i32 s36, s79, s59
	v_lshl_add_u64 v[180:181], v[180:181], 0, s[28:29]
	s_mov_b32 m0, s36
	ds_read_b128 v[198:201], v189 offset:49152
	ds_read_b128 v[202:205], v242 offset:49152
	ds_read_b128 v[206:209], v189 offset:51200
	ds_read_b128 v[210:213], v242 offset:51200
	ds_read_b128 v[214:217], v189 offset:53248
	ds_read_b128 v[218:221], v242 offset:53248
	ds_read_b128 v[222:225], v189 offset:55296
	ds_read_b128 v[226:229], v242 offset:55296
	global_load_lds_dwordx4 v[180:181], off
	s_add_i32 m0, s36, 0x2000
	s_add_u32 s20, s20, 0x80080
	v_lshl_add_u64 v[180:181], v[230:231], 0, s[28:29]
	s_addc_u32 s21, s21, 0
	s_add_i32 s36, s80, s59
	global_load_lds_dwordx4 v[180:181], off
	v_lshl_add_u64 v[180:181], s[20:21], 0, v[148:149]
	s_mov_b32 m0, s36
	s_nop 0
	global_load_lds_dwordx4 v[180:181], off
	v_lshl_add_u64 v[180:181], s[20:21], 0, v[152:153]
	s_add_i32 m0, s36, 0x2000
	s_nop 0
	global_load_lds_dwordx4 v[180:181], off
	v_lshl_add_u64 v[180:181], v[232:233], 0, s[28:29]
	s_mov_b32 m0, s67
	s_nop 0
	global_load_lds_dwordx4 v[180:181], off
	v_lshl_add_u64 v[180:181], v[234:235], 0, s[28:29]
	s_mov_b32 m0, s68
	s_nop 0
	global_load_lds_dwordx4 v[180:181], off
	s_waitcnt vmcnt(8)
	s_waitcnt lgkmcnt(0)
	s_barrier
	s_setprio 1
	s_waitcnt lgkmcnt(0)
	v_mfma_f32_16x16x32_bf16 v[60:63], v[128:131], v[198:201], v[60:63]
	v_mfma_f32_16x16x32_bf16 v[28:31], v[136:139], v[198:201], v[28:31]
	v_mfma_f32_16x16x32_bf16 v[52:55], v[128:131], v[206:209], v[52:55]
	v_mfma_f32_16x16x32_bf16 v[20:23], v[136:139], v[206:209], v[20:23]
	v_mfma_f32_16x16x32_bf16 v[48:51], v[128:131], v[214:217], v[48:51]
	v_mfma_f32_16x16x32_bf16 v[16:19], v[136:139], v[214:217], v[16:19]
	v_mfma_f32_16x16x32_bf16 v[44:47], v[128:131], v[222:225], v[44:47]
	v_mfma_f32_16x16x32_bf16 v[8:11], v[136:139], v[222:225], v[8:11]
	v_mfma_f32_16x16x32_bf16 v[60:63], v[132:135], v[202:205], v[60:63]
	v_mfma_f32_16x16x32_bf16 v[28:31], v[140:143], v[202:205], v[28:31]
	v_mfma_f32_16x16x32_bf16 v[52:55], v[132:135], v[210:213], v[52:55]
	v_mfma_f32_16x16x32_bf16 v[20:23], v[140:143], v[210:213], v[20:23]
	v_mfma_f32_16x16x32_bf16 v[48:51], v[132:135], v[218:221], v[48:51]
	v_mfma_f32_16x16x32_bf16 v[16:19], v[140:143], v[218:221], v[16:19]
	v_mfma_f32_16x16x32_bf16 v[44:47], v[132:135], v[226:229], v[44:47]
	v_mfma_f32_16x16x32_bf16 v[8:11], v[140:143], v[226:229], v[8:11]
	s_setprio 0
	s_setprio 1
	v_mfma_f32_16x16x32_bf16 v[56:59], v[168:171], v[198:201], v[56:59]
	v_mfma_f32_16x16x32_bf16 v[24:27], v[176:179], v[198:201], v[24:27]
	v_mfma_f32_16x16x32_bf16 v[40:43], v[168:171], v[206:209], v[40:43]
	v_mfma_f32_16x16x32_bf16 v[12:15], v[176:179], v[206:209], v[12:15]
	v_mfma_f32_16x16x32_bf16 v[36:39], v[168:171], v[214:217], v[36:39]
	v_mfma_f32_16x16x32_bf16 v[4:7], v[176:179], v[214:217], v[4:7]
	v_mfma_f32_16x16x32_bf16 v[32:35], v[168:171], v[222:225], v[32:35]
	v_mfma_f32_16x16x32_bf16 v[0:3], v[176:179], v[222:225], v[0:3]
	v_mfma_f32_16x16x32_bf16 v[56:59], v[172:175], v[202:205], v[56:59]
	v_mfma_f32_16x16x32_bf16 v[24:27], v[194:197], v[202:205], v[24:27]
	v_mfma_f32_16x16x32_bf16 v[40:43], v[172:175], v[210:213], v[40:43]
	v_mfma_f32_16x16x32_bf16 v[12:15], v[194:197], v[210:213], v[12:15]
	v_mfma_f32_16x16x32_bf16 v[36:39], v[172:175], v[218:221], v[36:39]
	v_mfma_f32_16x16x32_bf16 v[4:7], v[194:197], v[218:221], v[4:7]
	v_mfma_f32_16x16x32_bf16 v[32:35], v[172:175], v[226:229], v[32:35]
	v_mfma_f32_16x16x32_bf16 v[0:3], v[194:197], v[226:229], v[0:3]
	s_setprio 0
	s_barrier
	s_add_i32 s78, s78, 2
	s_add_u32 s18, s18, 0x100
	s_addc_u32 s19, s19, 0
	s_add_u32 s76, s76, 0x100
	s_addc_u32 s77, s77, 0

; #define PG8_STAGE(bufoff, gbase, voff) do { _Pragma("unroll") for (int _i = 0; _i < 2; ++_i) \
;         __builtin_amdgcn_global_load_lds((const unsigned*)((const char*)(gbase) + (voff)[_i]), (PG8_LAS unsigned*)(lds + (bufoff) + ldsw + _i * 8192), 16, 0, 0); } while (0)
; #define PG8_LDA(dst, b, h) do { _Pragma("unroll") for (int m = 0; m < 4; ++m) _Pragma("unroll") for (int k = 0; k < 2; ++k) dst[m][k] = *(const PG8_LAS bf16x8*)(lds + PG8_SA(b, h) + aoff + m * 2048 + k * 1024); } while (0)
; #define PG8_LDB(dst, b, h) do { _Pragma("unroll") for (int n = 0; n < 2; ++n) _Pragma("unroll") for (int k = 0; k < 2; ++k) dst[n][k] = *(const PG8_LAS bf16x8*)(lds + PG8_SB(b, h) + boff + n * 2048 + k * 1024); } while (0)
; #define PG8_MMA(ai, bj, At, Bt) do { __builtin_amdgcn_s_setprio(1); _Pragma("unroll") for (int m = 0; m < 4; ++m) _Pragma("unroll") for (int n = 0; n < 2; ++n) _Pragma("unroll") for (int k = 0; k < 2; ++k) \
;         acc[ai][bj][m][n] = __builtin_amdgcn_mfma_f32_16x16x32_bf16(Bt[n][k], At[m][k], acc[ai][bj][m][n], 0, 0, 0); __builtin_amdgcn_s_setprio(0); } while (0)
; template <class Epi, class Sched, bool ALIGN_EPI = false, bool SP2 = false>
; __device__ __forceinline__ void gemm_phase(PG8_LAS unsigned char* lds, const Gemm g, const Sched& S, const Epi& E) {
;     ...
;         const bool has_next = S.next(ui + 1, nxt);
;         const char* nA = has_next ? (const char*)(nxt.seg ? g.A2 : g.A) + (size_t)nxt.pm * tstep : cA; const char* nB = has_next ? (const char*)(nxt.seg ? g.Bt2 : g.Bt) + (size_t)nxt.pn * tstep : cB;
;         for (int t = 0; t < nt; t += 2) {
;             const bool last = (t == nt - 2);
;             const char* a1 = cA + (size_t)(t + 1) * kstep;
;             const char* a2 = last ? nA : cA + (size_t)(t + 2) * kstep; const char* b2 = last ? nB : cB + (size_t)(t + 2) * kstep;
;             const char* a3 = a2 + kstep; const char* b3 = b2 + kstep;
;             if (last && has_next) S.a_ready(nxt);
;             if constexpr (SP2) {
;             PG8_LDB(B0, 0, 0); PG8_LDB(B1, 0, 1); PG8_SCHED; PG8_LDA(At, 0, 0); PG8_STAGE(PG8_SA(1, 1), a1 + hstep, voffA);
;             PG8_WAIT_V(8); PG8_WAIT_L(0); PG8_BAR; PG8_MMA(0, 0, At, B0); PG8_MMA(0, 1, At, B1); PG8_BAR; PG8_SCHED;
;             PG8_LDA(At, 0, 1); PG8_STAGE(PG8_SB(0, 0), b2, voffB); PG8_STAGE(PG8_SB(0, 1), b2 + hstep, voffB); PG8_STAGE(PG8_SA(0, 0), a2, voffA);
.LBB0_1059:
	s_add_u32 s24, s24, 0x158080
	s_addc_u32 s25, s25, 0
	s_add_u32 s58, s26, 0x100
	v_mov_b32_e32 v0, 0
	s_addc_u32 s59, s27, 0
	s_mov_b32 s60, -2
	ds_read_b128 v[154:157], v150
	ds_read_b128 v[160:163], v151
	ds_read_b128 v[164:167], v150 offset:2048
	ds_read_b128 v[168:171], v151 offset:2048
	ds_read_b128 v[172:175], v150 offset:16384
	ds_read_b128 v[176:179], v151 offset:16384
	ds_read_b128 v[180:183], v150 offset:18432
	ds_read_b128 v[184:187], v151 offset:18432
	s_add_u32 s26, s24, 0xffea8080
	s_addc_u32 s27, s25, -1
	s_cmpk_eq_i32 s60, 0x52
	s_cselect_b32 s29, s3, s27
	s_cselect_b32 s28, s2, s26
	s_cselect_b32 s27, s23, s59
	s_cselect_b32 s26, s22, s58
	v_lshl_add_u64 v[146:147], s[24:25], 0, v[136:137]
	s_add_i32 m0, s40, 0xc000
	ds_read_b128 v[188:191], v152
	ds_read_b128 v[192:195], v242
	ds_read_b128 v[196:199], v152 offset:2048
	ds_read_b128 v[200:203], v242 offset:2048
	ds_read_b128 v[204:207], v152 offset:4096
	ds_read_b128 v[208:211], v242 offset:4096
	ds_read_b128 v[212:215], v152 offset:6144
	ds_read_b128 v[216:219], v242 offset:6144
	global_load_lds_dwordx4 v[146:147], off
	v_lshl_add_u64 v[146:147], s[24:25], 0, v[138:139]
	s_add_i32 m0, s40, 0xe000
	s_nop 0
	global_load_lds_dwordx4 v[146:147], off
	s_waitcnt vmcnt(8)
	s_waitcnt lgkmcnt(0)
	s_barrier
	s_setprio 1
	s_waitcnt lgkmcnt(0)
	v_mfma_f32_16x16x32_bf16 v[124:127], v[154:157], v[188:191], 0
	v_mfma_f32_16x16x32_bf16 v[120:123], v[164:167], v[188:191], 0
	v_mfma_f32_16x16x32_bf16 v[116:119], v[154:157], v[196:199], 0
	v_mfma_f32_16x16x32_bf16 v[108:111], v[164:167], v[196:199], 0
	v_mfma_f32_16x16x32_bf16 v[100:103], v[154:157], v[204:207], 0
	v_mfma_f32_16x16x32_bf16 v[92:95], v[164:167], v[204:207], 0
	v_mfma_f32_16x16x32_bf16 v[84:87], v[154:157], v[212:215], 0
	v_mfma_f32_16x16x32_bf16 v[76:79], v[164:167], v[212:215], 0
	v_mfma_f32_16x16x32_bf16 v[124:127], v[160:163], v[192:195], v[124:127]
	v_mfma_f32_16x16x32_bf16 v[120:123], v[168:171], v[192:195], v[120:123]
	v_mfma_f32_16x16x32_bf16 v[116:119], v[160:163], v[200:203], v[116:119]
	v_mfma_f32_16x16x32_bf16 v[108:111], v[168:171], v[200:203], v[108:111]
	v_mfma_f32_16x16x32_bf16 v[100:103], v[160:163], v[208:211], v[100:103]
	v_mfma_f32_16x16x32_bf16 v[92:95], v[168:171], v[208:211], v[92:95]
	v_mfma_f32_16x16x32_bf16 v[84:87], v[160:163], v[216:219], v[84:87]
	v_mfma_f32_16x16x32_bf16 v[76:79], v[168:171], v[216:219], v[76:79]
	s_setprio 0
	s_setprio 1
	v_mfma_f32_16x16x32_bf16 v[112:115], v[172:175], v[188:191], 0
	v_mfma_f32_16x16x32_bf16 v[104:107], v[180:183], v[188:191], 0
	v_mfma_f32_16x16x32_bf16 v[96:99], v[172:175], v[196:199], 0
	v_mfma_f32_16x16x32_bf16 v[88:91], v[180:183], v[196:199], 0
	v_mfma_f32_16x16x32_bf16 v[80:83], v[172:175], v[204:207], 0
	v_mfma_f32_16x16x32_bf16 v[72:75], v[180:183], v[204:207], 0
	v_mfma_f32_16x16x32_bf16 v[68:71], v[172:175], v[212:215], 0
	v_mfma_f32_16x16x32_bf16 v[64:67], v[180:183], v[212:215], 0
	v_mfma_f32_16x16x32_bf16 v[112:115], v[176:179], v[192:195], v[112:115]
	v_mfma_f32_16x16x32_bf16 v[104:107], v[184:187], v[192:195], v[104:107]
	v_mfma_f32_16x16x32_bf16 v[96:99], v[176:179], v[200:203], v[96:99]
	v_mfma_f32_16x16x32_bf16 v[88:91], v[184:187], v[200:203], v[88:91]
	v_mfma_f32_16x16x32_bf16 v[80:83], v[176:179], v[208:211], v[80:83]
	v_mfma_f32_16x16x32_bf16 v[72:75], v[184:187], v[208:211], v[72:75]
	v_mfma_f32_16x16x32_bf16 v[68:71], v[176:179], v[216:219], v[68:71]
	v_mfma_f32_16x16x32_bf16 v[64:67], v[184:187], v[216:219], v[64:67]
	s_setprio 0
	s_barrier
	s_add_i32 s36, s48, s39
	v_lshl_add_u64 v[146:147], s[26:27], 0, v[130:131]
	s_mov_b32 m0, s36
	ds_read_b128 v[188:191], v152 offset:16384
	ds_read_b128 v[192:195], v242 offset:16384
	ds_read_b128 v[196:199], v152 offset:18432
	ds_read_b128 v[200:203], v242 offset:18432
	ds_read_b128 v[204:207], v152 offset:20480
	ds_read_b128 v[208:211], v242 offset:20480
	ds_read_b128 v[212:215], v152 offset:22528
	ds_read_b128 v[216:219], v242 offset:22528
	global_load_lds_dwordx4 v[146:147], off
	s_add_i32 m0, s36, 0x2000
	s_add_u32 s36, s26, 0x158000
	v_lshl_add_u64 v[220:221], s[26:27], 0, v[134:135]
	s_addc_u32 s37, s27, 0
	s_add_i32 s61, s49, s39
	global_load_lds_dwordx4 v[220:221], off
	v_lshl_add_u64 v[222:223], s[36:37], 0, v[130:131]
	s_mov_b32 m0, s61
	v_lshl_add_u64 v[224:225], s[28:29], 0, v[132:133]
	global_load_lds_dwordx4 v[222:223], off
	v_lshl_add_u64 v[222:223], s[36:37], 0, v[134:135]
	s_add_i32 m0, s61, 0x2000
	s_nop 0
	global_load_lds_dwordx4 v[222:223], off
	v_lshl_add_u64 v[222:223], s[28:29], 0, v[128:129]
	s_mov_b32 m0, s40
	s_nop 0
	global_load_lds_dwordx4 v[222:223], off
	s_mov_b32 m0, s41
	s_nop 0
	global_load_lds_dwordx4 v[224:225], off
	s_waitcnt vmcnt(8)
	s_waitcnt lgkmcnt(0)
	s_barrier
; #define PG8_STAGE(bufoff, gbase, voff) do { _Pragma("unroll") for (int _i = 0; _i < 2; ++_i) \
;         __builtin_amdgcn_global_load_lds((const unsigned*)((const char*)(gbase) + (voff)[_i]), (PG8_LAS unsigned*)(lds + (bufoff) + ldsw + _i * 8192), 16, 0, 0); } while (0)
; #define PG8_LDA(dst, b, h) do { _Pragma("unroll") for (int m = 0; m < 4; ++m) _Pragma("unroll") for (int k = 0; k < 2; ++k) dst[m][k] = *(const PG8_LAS bf16x8*)(lds + PG8_SA(b, h) + aoff + m * 2048 + k * 1024); } while (0)
; #define PG8_LDB(dst, b, h) do { _Pragma("unroll") for (int n = 0; n < 2; ++n) _Pragma("unroll") for (int k = 0; k < 2; ++k) dst[n][k] = *(const PG8_LAS bf16x8*)(lds + PG8_SB(b, h) + boff + n * 2048 + k * 1024); } while (0)
; #define PG8_MMA(ai, bj, At, Bt) do { __builtin_amdgcn_s_setprio(1); _Pragma("unroll") for (int m = 0; m < 4; ++m) _Pragma("unroll") for (int n = 0; n < 2; ++n) _Pragma("unroll") for (int k = 0; k < 2; ++k) \
;         acc[ai][bj][m][n] = __builtin_amdgcn_mfma_f32_16x16x32_bf16(Bt[n][k], At[m][k], acc[ai][bj][m][n], 0, 0, 0); __builtin_amdgcn_s_setprio(0); } while (0)
; #define PG8_WAIT_V(n) asm volatile("s_waitcnt vmcnt(" #n ")" ::: "memory")
; #define PG8_WAIT_L(n) asm volatile("s_waitcnt lgkmcnt(" #n ")" ::: "memory")
; #define PG8_BAR __builtin_amdgcn_s_barrier()
; #define PG8_SCHED __builtin_amdgcn_sched_barrier(0)
; template <class Epi, class Sched, bool ALIGN_EPI = false, bool SP2 = false>
; __device__ __forceinline__ void gemm_phase(PG8_LAS unsigned char* lds, const Gemm g, const Sched& S, const Epi& E) {
;     ...
;             PG8_WAIT_V(8); PG8_WAIT_L(0); PG8_BAR; PG8_MMA(1, 0, At, B0); PG8_MMA(1, 1, At, B1); PG8_BAR; PG8_SCHED;
;             PG8_LDB(B0, 1, 0); PG8_LDB(B1, 1, 1); PG8_SCHED; PG8_LDA(At, 1, 0); PG8_STAGE(PG8_SA(0, 1), a2 + hstep, voffA);
;             PG8_WAIT_V(8); PG8_WAIT_L(0); PG8_BAR; PG8_MMA(0, 0, At, B0); PG8_MMA(0, 1, At, B1); PG8_BAR; PG8_SCHED;
	s_setprio 1
	s_waitcnt lgkmcnt(0)
	v_mfma_f32_16x16x32_bf16 v[60:63], v[154:157], v[188:191], 0
	v_mfma_f32_16x16x32_bf16 v[56:59], v[164:167], v[188:191], 0
	v_mfma_f32_16x16x32_bf16 v[52:55], v[154:157], v[196:199], 0
	v_mfma_f32_16x16x32_bf16 v[44:47], v[164:167], v[196:199], 0
	v_mfma_f32_16x16x32_bf16 v[36:39], v[154:157], v[204:207], 0
	v_mfma_f32_16x16x32_bf16 v[28:31], v[164:167], v[204:207], 0
	v_mfma_f32_16x16x32_bf16 v[20:23], v[154:157], v[212:215], 0
	v_mfma_f32_16x16x32_bf16 v[12:15], v[164:167], v[212:215], 0
	v_mfma_f32_16x16x32_bf16 v[60:63], v[160:163], v[192:195], v[60:63]
	v_mfma_f32_16x16x32_bf16 v[56:59], v[168:171], v[192:195], v[56:59]
	v_mfma_f32_16x16x32_bf16 v[52:55], v[160:163], v[200:203], v[52:55]
	v_mfma_f32_16x16x32_bf16 v[44:47], v[168:171], v[200:203], v[44:47]
	v_mfma_f32_16x16x32_bf16 v[36:39], v[160:163], v[208:211], v[36:39]
	v_mfma_f32_16x16x32_bf16 v[28:31], v[168:171], v[208:211], v[28:31]
	v_mfma_f32_16x16x32_bf16 v[20:23], v[160:163], v[216:219], v[20:23]
	v_mfma_f32_16x16x32_bf16 v[12:15], v[168:171], v[216:219], v[12:15]
	s_setprio 0
	s_setprio 1
	v_mfma_f32_16x16x32_bf16 v[48:51], v[172:175], v[188:191], 0
	v_mfma_f32_16x16x32_bf16 v[40:43], v[180:183], v[188:191], 0
	v_mfma_f32_16x16x32_bf16 v[32:35], v[172:175], v[196:199], 0
	v_mfma_f32_16x16x32_bf16 v[24:27], v[180:183], v[196:199], 0
	v_mfma_f32_16x16x32_bf16 v[16:19], v[172:175], v[204:207], 0
	v_mfma_f32_16x16x32_bf16 v[8:11], v[180:183], v[204:207], 0
	v_mfma_f32_16x16x32_bf16 v[4:7], v[172:175], v[212:215], 0
	v_mfma_f32_16x16x32_bf16 v[0:3], v[180:183], v[212:215], 0
	v_mfma_f32_16x16x32_bf16 v[48:51], v[176:179], v[192:195], v[48:51]
	v_mfma_f32_16x16x32_bf16 v[40:43], v[184:187], v[192:195], v[40:43]
	v_mfma_f32_16x16x32_bf16 v[32:35], v[176:179], v[200:203], v[32:35]
	v_mfma_f32_16x16x32_bf16 v[24:27], v[184:187], v[200:203], v[24:27]
	v_mfma_f32_16x16x32_bf16 v[16:19], v[176:179], v[208:211], v[16:19]
	v_mfma_f32_16x16x32_bf16 v[8:11], v[184:187], v[208:211], v[8:11]
	v_mfma_f32_16x16x32_bf16 v[4:7], v[176:179], v[216:219], v[4:7]
	v_mfma_f32_16x16x32_bf16 v[0:3], v[184:187], v[216:219], v[0:3]
	s_setprio 0
	s_barrier
	s_add_i32 s36, 0, 0x18000
	v_add_u32_e32 v153, s36, v148
	s_add_i32 s37, 0, 0x1c000
	ds_read_b128 v[154:157], v150 offset:32768
	ds_read_b128 v[160:163], v151 offset:32768
	ds_read_b128 v[164:167], v150 offset:34816
	ds_read_b128 v[168:171], v151 offset:34816
	v_add_u32_e32 v153, s37, v148
	ds_read_b128 v[172:175], v150 offset:49152
	ds_read_b128 v[176:179], v151 offset:49152
	ds_read_b128 v[180:183], v150 offset:51200
	ds_read_b128 v[184:187], v151 offset:51200
	s_add_u32 s28, s28, 0x158000
	s_addc_u32 s29, s29, 0
	s_mov_b32 m0, s42
	v_lshl_add_u64 v[226:227], s[28:29], 0, v[128:129]
	ds_read_b128 v[188:191], v152 offset:32768
	ds_read_b128 v[192:195], v242 offset:32768
	ds_read_b128 v[196:199], v152 offset:34816
	ds_read_b128 v[200:203], v242 offset:34816
	ds_read_b128 v[204:207], v152 offset:36864
	ds_read_b128 v[208:211], v242 offset:36864
	ds_read_b128 v[212:215], v152 offset:38912
	ds_read_b128 v[216:219], v242 offset:38912
	global_load_lds_dwordx4 v[226:227], off
	v_lshl_add_u64 v[226:227], s[28:29], 0, v[132:133]
	s_mov_b32 m0, s43
	s_nop 0
	global_load_lds_dwordx4 v[226:227], off
	s_waitcnt vmcnt(8)
	s_waitcnt lgkmcnt(0)
	s_barrier
	s_setprio 1
	s_waitcnt lgkmcnt(0)
	v_mfma_f32_16x16x32_bf16 v[124:127], v[154:157], v[188:191], v[124:127]
	v_mfma_f32_16x16x32_bf16 v[120:123], v[164:167], v[188:191], v[120:123]
	v_mfma_f32_16x16x32_bf16 v[116:119], v[154:157], v[196:199], v[116:119]
	v_mfma_f32_16x16x32_bf16 v[108:111], v[164:167], v[196:199], v[108:111]
	v_mfma_f32_16x16x32_bf16 v[100:103], v[154:157], v[204:207], v[100:103]
	v_mfma_f32_16x16x32_bf16 v[92:95], v[164:167], v[204:207], v[92:95]
	v_mfma_f32_16x16x32_bf16 v[84:87], v[154:157], v[212:215], v[84:87]
	v_mfma_f32_16x16x32_bf16 v[76:79], v[164:167], v[212:215], v[76:79]
	v_mfma_f32_16x16x32_bf16 v[124:127], v[160:163], v[192:195], v[124:127]
	v_mfma_f32_16x16x32_bf16 v[120:123], v[168:171], v[192:195], v[120:123]
	v_mfma_f32_16x16x32_bf16 v[116:119], v[160:163], v[200:203], v[116:119]
	v_mfma_f32_16x16x32_bf16 v[108:111], v[168:171], v[200:203], v[108:111]
	v_mfma_f32_16x16x32_bf16 v[100:103], v[160:163], v[208:211], v[100:103]
	v_mfma_f32_16x16x32_bf16 v[92:95], v[168:171], v[208:211], v[92:95]
	v_mfma_f32_16x16x32_bf16 v[84:87], v[160:163], v[216:219], v[84:87]
	v_mfma_f32_16x16x32_bf16 v[76:79], v[168:171], v[216:219], v[76:79]
	s_setprio 0
	s_setprio 1
	v_mfma_f32_16x16x32_bf16 v[112:115], v[172:175], v[188:191], v[112:115]
	v_mfma_f32_16x16x32_bf16 v[104:107], v[180:183], v[188:191], v[104:107]
	v_mfma_f32_16x16x32_bf16 v[96:99], v[172:175], v[196:199], v[96:99]
	v_mfma_f32_16x16x32_bf16 v[88:91], v[180:183], v[196:199], v[88:91]
	v_mfma_f32_16x16x32_bf16 v[80:83], v[172:175], v[204:207], v[80:83]
	v_mfma_f32_16x16x32_bf16 v[72:75], v[180:183], v[204:207], v[72:75]
	v_mfma_f32_16x16x32_bf16 v[68:71], v[172:175], v[212:215], v[68:71]
	v_mfma_f32_16x16x32_bf16 v[64:67], v[180:183], v[212:215], v[64:67]
	v_mfma_f32_16x16x32_bf16 v[112:115], v[176:179], v[192:195], v[112:115]
	v_mfma_f32_16x16x32_bf16 v[104:107], v[184:187], v[192:195], v[104:107]
	v_mfma_f32_16x16x32_bf16 v[96:99], v[176:179], v[200:203], v[96:99]
	v_mfma_f32_16x16x32_bf16 v[88:91], v[184:187], v[200:203], v[88:91]
	v_mfma_f32_16x16x32_bf16 v[80:83], v[176:179], v[208:211], v[80:83]
	v_mfma_f32_16x16x32_bf16 v[72:75], v[184:187], v[208:211], v[72:75]
	v_mfma_f32_16x16x32_bf16 v[68:71], v[176:179], v[216:219], v[68:71]
	v_mfma_f32_16x16x32_bf16 v[64:67], v[184:187], v[216:219], v[64:67]
	s_setprio 0
	s_barrier
; #define PG8_STAGE(bufoff, gbase, voff) do { _Pragma("unroll") for (int _i = 0; _i < 2; ++_i) \
;         __builtin_amdgcn_global_load_lds((const unsigned*)((const char*)(gbase) + (voff)[_i]), (PG8_LAS unsigned*)(lds + (bufoff) + ldsw + _i * 8192), 16, 0, 0); } while (0)
; #define PG8_LDA(dst, b, h) do { _Pragma("unroll") for (int m = 0; m < 4; ++m) _Pragma("unroll") for (int k = 0; k < 2; ++k) dst[m][k] = *(const PG8_LAS bf16x8*)(lds + PG8_SA(b, h) + aoff + m * 2048 + k * 1024); } while (0)
; #define PG8_MMA(ai, bj, At, Bt) do { __builtin_amdgcn_s_setprio(1); _Pragma("unroll") for (int m = 0; m < 4; ++m) _Pragma("unroll") for (int n = 0; n < 2; ++n) _Pragma("unroll") for (int k = 0; k < 2; ++k) \
;         acc[ai][bj][m][n] = __builtin_amdgcn_mfma_f32_16x16x32_bf16(Bt[n][k], At[m][k], acc[ai][bj][m][n], 0, 0, 0); __builtin_amdgcn_s_setprio(0); } while (0)
; #define PG8_WAIT_V(n) asm volatile("s_waitcnt vmcnt(" #n ")" ::: "memory")
; #define PG8_WAIT_L(n) asm volatile("s_waitcnt lgkmcnt(" #n ")" ::: "memory")
; #define PG8_BAR __builtin_amdgcn_s_barrier()
; #define PG8_SCHED __builtin_amdgcn_sched_barrier(0)
; template <class Epi, class Sched, bool ALIGN_EPI = false, bool SP2 = false>
; __device__ __forceinline__ void gemm_phase(PG8_LAS unsigned char* lds, const Gemm g, const Sched& S, const Epi& E) {
;     ...
;         for (int t = 0; t < nt; t += 2) {
;     ...
;             PG8_LDA(At, 1, 1); PG8_STAGE(PG8_SB(1, 0), b3, voffB); PG8_STAGE(PG8_SB(1, 1), b3 + hstep, voffB); PG8_STAGE(PG8_SA(1, 0), a3, voffA);
;             PG8_WAIT_V(8); PG8_WAIT_L(0); PG8_BAR; PG8_MMA(1, 0, At, B0); PG8_MMA(1, 1, At, B1); PG8_BAR; PG8_SCHED;
	s_add_i32 s28, s36, s39
	v_lshl_add_u64 v[146:147], v[146:147], 0, s[10:11]
	s_mov_b32 m0, s28
	ds_read_b128 v[188:191], v152 offset:49152
	ds_read_b128 v[192:195], v242 offset:49152
	ds_read_b128 v[196:199], v152 offset:51200
	ds_read_b128 v[200:203], v242 offset:51200
	ds_read_b128 v[204:207], v152 offset:53248
	ds_read_b128 v[208:211], v242 offset:53248
	ds_read_b128 v[212:215], v152 offset:55296
	ds_read_b128 v[216:219], v242 offset:55296
	global_load_lds_dwordx4 v[146:147], off
	s_add_i32 m0, s28, 0x2000
	s_add_u32 s26, s26, 0x158080
	v_lshl_add_u64 v[146:147], v[220:221], 0, s[10:11]
	s_addc_u32 s27, s27, 0
	s_add_i32 s28, s37, s39
	global_load_lds_dwordx4 v[146:147], off
	v_lshl_add_u64 v[146:147], s[26:27], 0, v[130:131]
	s_mov_b32 m0, s28
	s_nop 0
	global_load_lds_dwordx4 v[146:147], off
	v_lshl_add_u64 v[146:147], s[26:27], 0, v[134:135]
	s_add_i32 m0, s28, 0x2000
	s_nop 0
	global_load_lds_dwordx4 v[146:147], off
	v_lshl_add_u64 v[146:147], v[222:223], 0, s[10:11]
	s_mov_b32 m0, s45
	s_nop 0
	global_load_lds_dwordx4 v[146:147], off
	v_lshl_add_u64 v[146:147], v[224:225], 0, s[10:11]
	s_mov_b32 m0, s46
	s_nop 0
	global_load_lds_dwordx4 v[146:147], off
	s_waitcnt vmcnt(8)
	s_waitcnt lgkmcnt(0)
	s_barrier
	s_setprio 1
	s_waitcnt lgkmcnt(0)
	v_mfma_f32_16x16x32_bf16 v[60:63], v[154:157], v[188:191], v[60:63]
	v_mfma_f32_16x16x32_bf16 v[56:59], v[164:167], v[188:191], v[56:59]
	v_mfma_f32_16x16x32_bf16 v[52:55], v[154:157], v[196:199], v[52:55]
	v_mfma_f32_16x16x32_bf16 v[44:47], v[164:167], v[196:199], v[44:47]
	v_mfma_f32_16x16x32_bf16 v[36:39], v[154:157], v[204:207], v[36:39]
	v_mfma_f32_16x16x32_bf16 v[28:31], v[164:167], v[204:207], v[28:31]
	v_mfma_f32_16x16x32_bf16 v[20:23], v[154:157], v[212:215], v[20:23]
	v_mfma_f32_16x16x32_bf16 v[12:15], v[164:167], v[212:215], v[12:15]
	v_mfma_f32_16x16x32_bf16 v[60:63], v[160:163], v[192:195], v[60:63]
	v_mfma_f32_16x16x32_bf16 v[56:59], v[168:171], v[192:195], v[56:59]
	v_mfma_f32_16x16x32_bf16 v[52:55], v[160:163], v[200:203], v[52:55]
	v_mfma_f32_16x16x32_bf16 v[44:47], v[168:171], v[200:203], v[44:47]
	v_mfma_f32_16x16x32_bf16 v[36:39], v[160:163], v[208:211], v[36:39]
	v_mfma_f32_16x16x32_bf16 v[28:31], v[168:171], v[208:211], v[28:31]
	v_mfma_f32_16x16x32_bf16 v[20:23], v[160:163], v[216:219], v[20:23]
	v_mfma_f32_16x16x32_bf16 v[12:15], v[168:171], v[216:219], v[12:15]
	s_setprio 0
	s_setprio 1
	v_mfma_f32_16x16x32_bf16 v[48:51], v[172:175], v[188:191], v[48:51]
	v_mfma_f32_16x16x32_bf16 v[40:43], v[180:183], v[188:191], v[40:43]
	v_mfma_f32_16x16x32_bf16 v[32:35], v[172:175], v[196:199], v[32:35]
	v_mfma_f32_16x16x32_bf16 v[24:27], v[180:183], v[196:199], v[24:27]
	v_mfma_f32_16x16x32_bf16 v[16:19], v[172:175], v[204:207], v[16:19]
	v_mfma_f32_16x16x32_bf16 v[8:11], v[180:183], v[204:207], v[8:11]
	v_mfma_f32_16x16x32_bf16 v[4:7], v[172:175], v[212:215], v[4:7]
	v_mfma_f32_16x16x32_bf16 v[0:3], v[180:183], v[212:215], v[0:3]
	v_mfma_f32_16x16x32_bf16 v[48:51], v[176:179], v[192:195], v[48:51]
	v_mfma_f32_16x16x32_bf16 v[40:43], v[184:187], v[192:195], v[40:43]
	v_mfma_f32_16x16x32_bf16 v[32:35], v[176:179], v[200:203], v[32:35]
	v_mfma_f32_16x16x32_bf16 v[24:27], v[184:187], v[200:203], v[24:27]
	v_mfma_f32_16x16x32_bf16 v[16:19], v[176:179], v[208:211], v[16:19]
	v_mfma_f32_16x16x32_bf16 v[8:11], v[184:187], v[208:211], v[8:11]
	v_mfma_f32_16x16x32_bf16 v[4:7], v[176:179], v[216:219], v[4:7]
	v_mfma_f32_16x16x32_bf16 v[0:3], v[184:187], v[216:219], v[0:3]
	s_setprio 0
	s_barrier
	s_add_i32 s60, s60, 2
	s_add_u32 s24, s24, 0x100
	s_addc_u32 s25, s25, 0
	s_add_u32 s58, s58, 0x100
	s_addc_u32 s59, s59, 0
